# P2: half of the workgroups run the pooling body after their attention units instead of before (pooling's HBM burst halves and overlaps the other half's attention)
# speedup vs baseline: 1.0019x; 1.0019x over previous
; __global__ void __launch_bounds__(NTHR, 2) hybrid_fwd(Args args) {
;     ...
;         const int rpb = (T + G - 1) / G, rows_per = (rpb + NWAVES - 1) / NWAVES;
;         const int gI = lane >> 4, w = 2 << gI;
;         const int t_b = hb * rpb + wave * rows_per; int nr = rpb - wave * rows_per; if (nr > rows_per) nr = rows_per; if (t_b + nr > T) nr = T - t_b;
;         u32x4 qn[16];
;         if (nr > 0) { const int sp0 = t_b & 2047, c0_ = (sp0 + 1) < w ? (sp0 + 1) : w;
; #pragma unroll
;             for (int j = 0; j < 16; ++j) qn[j] = *(const u32x4*)(UB + (size_t)(j < c0_ ? t_b - j : t_b) * 512 + lane * 8); }
.LBB0_370:
	s_mov_b32 s98, 0
	v_writelane_b32 v248, s98, 41
	s_mov_b64 s[8:9], s[18:19]
	s_mov_b32 s11, s20
	s_and_b32 s14, s11, 7
	s_mov_b32 s24, s2
	s_cmp_lg_u32 s14, 0
	s_cbranch_scc1 .LBB0_372
	s_ashr_i32 s15, s24, 31
	s_lshr_b32 s15, s15, 29
	s_add_i32 s15, s24, s15
	s_ashr_i32 s25, s15, 3
	s_and_b32 s15, s15, -8
	s_ashr_i32 s11, s11, 3
	s_sub_i32 s15, s24, s15
	s_mul_i32 s11, s15, s11
	s_add_i32 s24, s11, s25
.LBB0_372:
	s_add_i32 s25, s20, 0x7fff
	s_waitcnt lgkmcnt(0)
	s_waitcnt lgkmcnt(0)
	s_waitcnt lgkmcnt(0)
	s_waitcnt lgkmcnt(0)
	s_waitcnt lgkmcnt(0)
	s_waitcnt lgkmcnt(0)
	s_waitcnt lgkmcnt(0)
	s_waitcnt lgkmcnt(0)
	s_waitcnt lgkmcnt(0)
	s_waitcnt lgkmcnt(0)
	s_waitcnt lgkmcnt(0)
	s_waitcnt lgkmcnt(0)
	s_waitcnt lgkmcnt(0)
	s_waitcnt lgkmcnt(0)
	s_waitcnt lgkmcnt(0)
	s_waitcnt lgkmcnt(0)
	s_waitcnt lgkmcnt(0)
	s_waitcnt lgkmcnt(0)
	s_waitcnt lgkmcnt(0)
	s_abs_i32 s61, s20
	v_cvt_f32_u32_e32 v1, s61
	s_sub_i32 s27, 0, s61
	s_waitcnt lgkmcnt(0)
	v_rcp_iflag_f32_e32 v1, v1
	s_ashr_i32 s26, s25, 31
	s_abs_i32 s25, s25
	v_mul_f32_e32 v1, 0x4f7ffffe, v1
	v_cvt_u32_f32_e32 v1, v1
	s_xor_b32 s26, s26, s21
	s_mov_b32 s28, 1
	v_readfirstlane_b32 s62, v1
	s_mul_i32 s27, s27, s62
	s_mul_hi_u32 s10, s62, s27
	s_add_i32 s62, s62, s10
	s_mul_hi_u32 s10, s25, s62
	s_mul_i32 s11, s10, s61
	s_sub_i32 s11, s25, s11
	s_add_i32 s14, s10, 1
	s_sub_i32 s15, s11, s61
	s_cmp_ge_u32 s11, s61
	s_cselect_b32 s10, s14, s10
	s_cselect_b32 s11, s15, s11
	s_add_i32 s14, s10, 1
	s_cmp_ge_u32 s11, s61
	s_cselect_b32 s10, s14, s10
	s_xor_b32 s10, s10, s26
	s_sub_i32 s56, s10, s26
	s_add_i32 s10, s56, 7
	s_ashr_i32 s14, s10, 31
	s_lshr_b32 s14, s14, 29
	s_add_i32 s10, s10, s14
	s_ashr_i32 s14, s10, 3
	s_mul_i32 s11, s56, s24
	s_mul_i32 s15, s14, s74
	s_add_i32 s10, s15, s11
	s_sub_i32 s11, s56, s15
	s_min_i32 s57, s11, s14
	s_add_i32 s11, s57, s10
	s_sub_i32 s14, 0x8000, s10
	s_cmp_gt_i32 s11, 0x8000
	s_cselect_b32 s29, s14, s57
	v_mov_b32_e32 v0, v212
	s_cmp_lt_i32 s29, 1
	v_writelane_b32 v248, s15, 5
	s_cbranch_scc1 .LBB0_377
	s_cmp_lg_u32 s29, 16
	s_cbranch_scc1 .Lpool_orig
	s_and_b32 s98, s10, 15
	s_cmp_lg_u32 s98, 0
	s_cbranch_scc1 .Lpool_orig
	s_cmp_lg_u32 s20, 0x100
	s_cbranch_scc1 .Lpool_body
	s_bitcmp1_b32 s2, 3
	s_cbranch_scc0 .Lpool_body
	v_writelane_b32 v248, s10, 40
	s_mov_b32 s98, 1
	v_writelane_b32 v248, s98, 41
	s_branch .LBB0_377
.Lpool_body:
	v_lshlrev_b32_e32 v0, 4, v212
	v_mov_b32_e32 v1, 0
	s_lshl_b32 s98, s10, 10
	s_add_u32 s14, s8, 0x15c00000
	s_addc_u32 s15, s9, 0
	s_add_u32 s14, s14, s98
	s_addc_u32 s15, s15, 0
	s_and_b32 s99, s10, 0x7ff
	s_sub_u32 s26, s14, 0x3000
	s_subb_u32 s27, s15, 0
	v_lshl_add_u64 v[2:3], s[26:27], 0, v[0:1]
	s_sub_u32 s26, s14, 0x1000
	s_subb_u32 s27, s15, 0
	v_lshl_add_u64 v[4:5], s[26:27], 0, v[0:1]
	s_add_u32 s26, s14, 0x1000
	s_addc_u32 s27, s15, 0
	v_lshl_add_u64 v[6:7], s[26:27], 0, v[0:1]
	s_add_u32 s26, s14, 0x3000
	s_addc_u32 s27, s15, 0
	v_lshl_add_u64 v[132:133], s[26:27], 0, v[0:1]
	s_cmp_eq_u32 s99, 0
	s_cbranch_scc1 .Lpool_ld_seqstart
	global_load_dwordx4 v[8:11], v[2:3], off offset:-3072 nt
	global_load_dwordx4 v[12:15], v[2:3], off offset:-2048 nt
	global_load_dwordx4 v[16:19], v[2:3], off offset:-1024 nt
	global_load_dwordx4 v[20:23], v[2:3], off nt
	global_load_dwordx4 v[24:27], v[2:3], off offset:1024 nt
	global_load_dwordx4 v[28:31], v[2:3], off offset:2048 nt
	global_load_dwordx4 v[32:35], v[2:3], off offset:3072 nt
	global_load_dwordx4 v[36:39], v[4:5], off offset:-4096 nt
	global_load_dwordx4 v[40:43], v[4:5], off offset:-3072 nt
	global_load_dwordx4 v[44:47], v[4:5], off offset:-2048 nt
	global_load_dwordx4 v[48:51], v[4:5], off offset:-1024 nt
	global_load_dwordx4 v[52:55], v[4:5], off nt
	global_load_dwordx4 v[56:59], v[4:5], off offset:1024 nt
	global_load_dwordx4 v[60:63], v[4:5], off offset:2048 nt
	global_load_dwordx4 v[64:67], v[4:5], off offset:3072 nt
	global_load_dwordx4 v[68:71], v[6:7], off offset:-4096 nt
	global_load_dwordx4 v[72:75], v[6:7], off offset:-3072 nt
	global_load_dwordx4 v[76:79], v[6:7], off offset:-2048 nt
	global_load_dwordx4 v[80:83], v[6:7], off offset:-1024 nt
	global_load_dwordx4 v[84:87], v[6:7], off nt
	global_load_dwordx4 v[88:91], v[6:7], off offset:1024 nt
	global_load_dwordx4 v[92:95], v[6:7], off offset:2048 nt
	global_load_dwordx4 v[96:99], v[6:7], off offset:3072 nt
	global_load_dwordx4 v[100:103], v[132:133], off offset:-4096 nt
	global_load_dwordx4 v[104:107], v[132:133], off offset:-3072 nt
	global_load_dwordx4 v[108:111], v[132:133], off offset:-2048 nt
	global_load_dwordx4 v[112:115], v[132:133], off offset:-1024 nt
	global_load_dwordx4 v[116:119], v[132:133], off nt
	global_load_dwordx4 v[120:123], v[132:133], off offset:1024 nt
	global_load_dwordx4 v[124:127], v[132:133], off offset:2048 nt
	global_load_dwordx4 v[128:131], v[132:133], off offset:3072 nt
	s_branch .Lpool_ld_done

; __device__ __forceinline__ unsigned pk2(float lo, float hi) { return pg8::cvt_pk_bf16(lo, hi); }
; __global__ void __launch_bounds__(NTHR, 2) hybrid_fwd(Args args) {
;     ...
;         for (int i = 0; i < nr; ++i) { const int t = t_b + i;
;             const int sp = t & 2047, cnt = (sp + 1) < w ? (sp + 1) : w;
;             u32x4 qv[16];
; #pragma unroll
;             for (int j = 0; j < 16; ++j) qv[j] = qn[j];
;             if (i + 1 < nr) { const int t1 = t + 1, sp1 = t1 & 2047, c1_ = (sp1 + 1) < w ? (sp1 + 1) : w;
; #pragma unroll
;                 for (int j = 0; j < 16; ++j) qn[j] = *(const u32x4*)(UB + (size_t)(j < c1_ ? t1 - j : t1) * 512 + lane * 8); }
;             float a[8];
; #pragma unroll
;             for (int e = 0; e < 8; ++e) a[e] = 0.f;
;             const u32x4 u0 = qv[0];
; #pragma unroll
;             for (int j = 0; j < 16; ++j) { const float mk = j < cnt ? 1.0f : 0.0f; const u32x4 q = qv[j];
;                 a[0] += mk * bflo(q.x); a[1] += mk * bfhi(q.x); a[2] += mk * bflo(q.y); a[3] += mk * bfhi(q.y); a[4] += mk * bflo(q.z); a[5] += mk * bfhi(q.z); a[6] += mk * bflo(q.w); a[7] += mk * bfhi(q.w); }
;             const float ic = 1.0f / (float)cnt;
;             u32x4 o; o.x = pk2(a[0] * ic - bflo(u0.x), a[1] * ic - bfhi(u0.x)); o.y = pk2(a[2] * ic - bflo(u0.y), a[3] * ic - bfhi(u0.y));
;             o.z = pk2(a[4] * ic - bflo(u0.z), a[5] * ic - bfhi(u0.z)); o.w = pk2(a[6] * ic - bflo(u0.w), a[7] * ic - bfhi(u0.w));
.Lpool_ld_done:
	v_lshrrev_b32_e32 v137, 4, v212
	v_cmp_lt_u32_e32 vcc, 0, v137
	s_nop 1
	v_cndmask_b32_e64 v134, 0, 1.0, vcc
	v_cmp_lt_u32_e32 vcc, 1, v137
	s_nop 1
	v_cndmask_b32_e64 v135, 0, 1.0, vcc
	v_cmp_lt_u32_e32 vcc, 2, v137
	s_nop 1
	v_cndmask_b32_e64 v136, 0, 1.0, vcc
	v_lshlrev_b32_e64 v137, v137, 2
	s_lshl_b32 s98, s10, 11
	s_add_u32 s26, s8, 0x3c00000
	s_addc_u32 s27, s9, 0
	s_add_u32 s26, s26, s98
	s_addc_u32 s27, s27, 0
	v_lshl_add_u64 v[138:139], s[26:27], 0, v[0:1]
	s_mov_b32 s100, 0xffff0000
	s_mov_b64 s[26:27], 0x1000
	s_waitcnt vmcnt(0)
	v_mov_b32_e32 v175, 0
	v_mov_b32_e32 v176, 0
	v_mov_b32_e32 v177, 0
	v_mov_b32_e32 v178, 0
	v_mov_b32_e32 v179, 0
	v_mov_b32_e32 v180, 0
	v_mov_b32_e32 v181, 0
	v_mov_b32_e32 v182, 0
	v_mov_b32_e32 v183, 0
	v_mov_b32_e32 v184, 0
	v_mov_b32_e32 v185, 0
	v_mov_b32_e32 v186, 0
	v_mov_b32_e32 v187, 0
	v_mov_b32_e32 v188, 0
	v_mov_b32_e32 v189, 0
	v_mov_b32_e32 v190, 0
	v_mov_b32_e32 v191, 0
	v_mov_b32_e32 v192, 0
	v_mov_b32_e32 v193, 0
	v_mov_b32_e32 v194, 0
	v_mov_b32_e32 v195, 0
	v_mov_b32_e32 v196, 0
	v_mov_b32_e32 v197, 0
	v_mov_b32_e32 v198, 0
	v_mov_b32_e32 v199, 0
	v_mov_b32_e32 v200, 0
	v_mov_b32_e32 v201, 0
	v_mov_b32_e32 v202, 0
	v_mov_b32_e32 v203, 0
	v_mov_b32_e32 v204, 0
	v_mov_b32_e32 v205, 0
	v_mov_b32_e32 v206, 0
	v_mov_b32_e32 v207, 0
	v_mov_b32_e32 v208, 0
	v_mov_b32_e32 v209, 0
	v_mov_b32_e32 v210, 0
	v_mov_b32_e32 v211, 0
	v_mov_b32_e32 v221, 0
	v_mov_b32_e32 v222, 0
	v_mov_b32_e32 v223, 0
	v_mov_b32_e32 v224, 0
	v_mov_b32_e32 v225, 0
	v_mov_b32_e32 v226, 0
	v_mov_b32_e32 v227, 0
	v_mov_b32_e32 v228, 0
	v_mov_b32_e32 v229, 0
	v_mov_b32_e32 v230, 0
	v_mov_b32_e32 v231, 0
	v_mov_b32_e32 v232, 0
	v_mov_b32_e32 v233, 0
	v_mov_b32_e32 v234, 0
	v_mov_b32_e32 v235, 0
	v_mov_b32_e32 v236, 0
	v_mov_b32_e32 v237, 0
	v_mov_b32_e32 v238, 0
	v_mov_b32_e32 v239, 0
	v_mov_b32_e32 v240, 0
	v_mov_b32_e32 v241, 0
	v_mov_b32_e32 v242, 0
	v_mov_b32_e32 v243, 0
	v_lshlrev_b32_e32 v0, 16, v8
	v_and_b32_e32 v1, s100, v8
	v_lshlrev_b32_e32 v172, 16, v9
	v_and_b32_e32 v173, s100, v9
	v_add_f32_e32 v214, v0, v175
	v_add_f32_e32 v215, v1, v176
	v_add_f32_e32 v216, v172, v177
	v_add_f32_e32 v217, v173, v178
	v_fma_f32 v244, v134, v179, v214
	v_fma_f32 v245, v134, v180, v215
	v_fma_f32 v246, v134, v181, v216
	v_fma_f32 v247, v134, v182, v217
	v_fma_f32 v249, v135, v187, v244
	v_fma_f32 v250, v135, v188, v245
	v_fma_f32 v251, v135, v189, v246
	v_fma_f32 v252, v135, v190, v247
	v_lshlrev_b32_e32 v253, 16, v12
	v_and_b32_e32 v254, s100, v12
	v_lshlrev_b32_e32 v255, 16, v13
	v_and_b32_e32 v179, s100, v13
	v_add_f32_e32 v180, v253, v0
	v_add_f32_e32 v181, v254, v1
	v_add_f32_e32 v182, v255, v172
	v_add_f32_e32 v187, v179, v173
	v_fma_f32 v188, v134, v183, v180
	v_fma_f32 v189, v134, v184, v181
	v_fma_f32 v190, v134, v185, v182
	v_fma_f32 v203, v134, v186, v187
	v_fma_f32 v204, v135, v191, v188
	v_fma_f32 v205, v135, v192, v189
	v_fma_f32 v206, v135, v193, v190
	v_fma_f32 v175, v135, v194, v203
	v_lshlrev_b32_e32 v176, 16, v16
	v_and_b32_e32 v177, s100, v16
	v_lshlrev_b32_e32 v178, 16, v17
	v_and_b32_e32 v183, s100, v17
	v_add_f32_e32 v184, v176, v253
	v_add_f32_e32 v185, v177, v254
	v_add_f32_e32 v186, v178, v255
	v_add_f32_e32 v191, v183, v179
	v_fma_f32 v192, v134, v214, v184
	v_fma_f32 v193, v134, v215, v185
	v_fma_f32 v194, v134, v216, v186
	v_fma_f32 v207, v134, v217, v191
	v_fma_f32 v208, v135, v195, v192
	v_fma_f32 v209, v135, v196, v193
	v_fma_f32 v210, v135, v197, v194
	v_fma_f32 v0, v135, v198, v207
	v_lshlrev_b32_e32 v1, 16, v20
	v_and_b32_e32 v172, s100, v20
	v_lshlrev_b32_e32 v173, 16, v21
	v_and_b32_e32 v214, s100, v21
	v_add_f32_e32 v215, v1, v176
	v_add_f32_e32 v216, v172, v177
	v_add_f32_e32 v217, v173, v178
	v_add_f32_e32 v195, v214, v183
	v_fma_f32 v196, v134, v180, v215
	v_fma_f32 v197, v134, v181, v216
	v_fma_f32 v198, v134, v182, v217
	v_fma_f32 v211, v134, v187, v195
	v_fma_f32 v221, v135, v199, v196
	v_fma_f32 v222, v135, v200, v197
	v_fma_f32 v223, v135, v201, v198
	v_fma_f32 v253, v135, v202, v211
	v_lshlrev_b32_e32 v254, 16, v24
	v_and_b32_e32 v255, s100, v24
	v_lshlrev_b32_e32 v179, 16, v25
	v_and_b32_e32 v180, s100, v25
	v_add_f32_e32 v181, v254, v1
	v_add_f32_e32 v182, v255, v172
	v_add_f32_e32 v187, v179, v173
	v_add_f32_e32 v199, v180, v214
	v_fma_f32 v200, v134, v184, v181
	v_fma_f32 v201, v134, v185, v182
	v_fma_f32 v202, v134, v186, v187
	v_fma_f32 v224, v134, v191, v199
	v_fma_f32 v225, v135, v244, v200
	v_fma_f32 v226, v135, v245, v201
	v_fma_f32 v227, v135, v246, v202
	v_fma_f32 v176, v135, v247, v224
	v_lshlrev_b32_e32 v177, 16, v28
	v_and_b32_e32 v178, s100, v28
	v_lshlrev_b32_e32 v183, 16, v29
	v_and_b32_e32 v184, s100, v29
	v_add_f32_e32 v185, v177, v254
	v_add_f32_e32 v186, v178, v255
	v_add_f32_e32 v191, v183, v179
	v_add_f32_e32 v244, v184, v180
	v_fma_f32 v245, v134, v215, v185
	v_fma_f32 v246, v134, v216, v186
	v_fma_f32 v247, v134, v217, v191
	v_fma_f32 v228, v134, v195, v244
	v_fma_f32 v229, v135, v188, v245
	v_fma_f32 v230, v135, v189, v246
	v_fma_f32 v231, v135, v190, v247
	v_fma_f32 v1, v135, v203, v228
	v_lshlrev_b32_e32 v172, 16, v32
	v_and_b32_e32 v173, s100, v32
	v_lshlrev_b32_e32 v214, 16, v33
	v_and_b32_e32 v215, s100, v33
	v_add_f32_e32 v216, v172, v177
	v_add_f32_e32 v217, v173, v178
	v_add_f32_e32 v195, v214, v183
	v_add_f32_e32 v188, v215, v184
	v_fma_f32 v189, v134, v181, v216
	v_fma_f32 v190, v134, v182, v217
	v_fma_f32 v203, v134, v187, v195
	v_fma_f32 v232, v134, v199, v188
	v_fma_f32 v233, v135, v192, v189
	v_fma_f32 v234, v135, v193, v190
	v_fma_f32 v235, v135, v194, v203
	v_fma_f32 v254, v135, v207, v232
	v_lshlrev_b32_e32 v255, 16, v36
; __device__ __forceinline__ unsigned pk2(float lo, float hi) { return pg8::cvt_pk_bf16(lo, hi); }
; __global__ void __launch_bounds__(NTHR, 2) hybrid_fwd(Args args) {
;     ...
;             float a[8];
; #pragma unroll
;             for (int e = 0; e < 8; ++e) a[e] = 0.f;
;             const u32x4 u0 = qv[0];
; #pragma unroll
;             for (int j = 0; j < 16; ++j) { const float mk = j < cnt ? 1.0f : 0.0f; const u32x4 q = qv[j];
;                 a[0] += mk * bflo(q.x); a[1] += mk * bfhi(q.x); a[2] += mk * bflo(q.y); a[3] += mk * bfhi(q.y); a[4] += mk * bflo(q.z); a[5] += mk * bfhi(q.z); a[6] += mk * bflo(q.w); a[7] += mk * bfhi(q.w); }
;             const float ic = 1.0f / (float)cnt;
;             u32x4 o; o.x = pk2(a[0] * ic - bflo(u0.x), a[1] * ic - bfhi(u0.x)); o.y = pk2(a[2] * ic - bflo(u0.y), a[3] * ic - bfhi(u0.y));
;             o.z = pk2(a[4] * ic - bflo(u0.z), a[5] * ic - bfhi(u0.z)); o.w = pk2(a[6] * ic - bflo(u0.w), a[7] * ic - bfhi(u0.w));
	v_and_b32_e32 v179, s100, v36
	v_lshlrev_b32_e32 v180, 16, v37
	v_and_b32_e32 v181, s100, v37
	v_add_f32_e32 v182, v255, v172
	v_add_f32_e32 v187, v179, v173
	v_add_f32_e32 v199, v180, v214
	v_add_f32_e32 v192, v181, v215
	v_fma_f32 v193, v134, v185, v182
	v_fma_f32 v194, v134, v186, v187
	v_fma_f32 v207, v134, v191, v199
	v_fma_f32 v236, v134, v244, v192
	v_fma_f32 v237, v135, v196, v193
	v_fma_f32 v238, v135, v197, v194
	v_fma_f32 v239, v135, v198, v207
	v_fma_f32 v177, v135, v211, v236
	v_lshlrev_b32_e32 v178, 16, v40
	v_and_b32_e32 v183, s100, v40
	v_lshlrev_b32_e32 v184, 16, v41
	v_and_b32_e32 v185, s100, v41
	v_add_f32_e32 v186, v178, v255
	v_add_f32_e32 v191, v183, v179
	v_add_f32_e32 v244, v184, v180
	v_add_f32_e32 v196, v185, v181
	v_fma_f32 v197, v134, v216, v186
	v_fma_f32 v198, v134, v217, v191
	v_fma_f32 v211, v134, v195, v244
	v_fma_f32 v240, v134, v188, v196
	v_fma_f32 v241, v135, v200, v197
	v_fma_f32 v242, v135, v201, v198
	v_fma_f32 v243, v135, v202, v211
	v_fma_f32 v172, v135, v224, v240
	v_lshlrev_b32_e32 v173, 16, v44
	v_and_b32_e32 v214, s100, v44
	v_lshlrev_b32_e32 v215, 16, v45
	v_and_b32_e32 v216, s100, v45
	v_add_f32_e32 v217, v173, v178
	v_add_f32_e32 v195, v214, v183
	v_add_f32_e32 v188, v215, v184
	v_add_f32_e32 v200, v216, v185
	v_fma_f32 v201, v134, v182, v217
	v_fma_f32 v202, v134, v187, v195
	v_fma_f32 v224, v134, v199, v188
	v_fma_f32 v249, v134, v192, v200
	v_fma_f32 v250, v135, v245, v201
	v_fma_f32 v251, v135, v246, v202
	v_fma_f32 v252, v135, v247, v224
	v_fma_f32 v255, v135, v228, v249
	v_lshlrev_b32_e32 v179, 16, v48
	v_and_b32_e32 v180, s100, v48
	v_lshlrev_b32_e32 v181, 16, v49
	v_and_b32_e32 v182, s100, v49
	v_add_f32_e32 v187, v179, v173
	v_add_f32_e32 v199, v180, v214
	v_add_f32_e32 v192, v181, v215
	v_add_f32_e32 v245, v182, v216
	v_fma_f32 v246, v134, v186, v187
	v_fma_f32 v247, v134, v191, v199
	v_fma_f32 v228, v134, v244, v192
	v_fma_f32 v204, v134, v196, v245
	v_fma_f32 v205, v135, v189, v246
	v_fma_f32 v206, v135, v190, v247
	v_fma_f32 v175, v135, v203, v228
	v_fma_f32 v178, v135, v232, v204
	v_lshlrev_b32_e32 v183, 16, v52
	v_and_b32_e32 v184, s100, v52
	v_lshlrev_b32_e32 v185, 16, v53
	v_and_b32_e32 v186, s100, v53
	v_add_f32_e32 v191, v183, v179
	v_add_f32_e32 v244, v184, v180
	v_add_f32_e32 v196, v185, v181
	v_add_f32_e32 v189, v186, v182
	v_fma_f32 v190, v134, v217, v191
	v_fma_f32 v203, v134, v195, v244
	v_fma_f32 v232, v134, v188, v196
	v_fma_f32 v208, v134, v200, v189
	v_fma_f32 v209, v135, v193, v190
	v_fma_f32 v210, v135, v194, v203
	v_fma_f32 v0, v135, v207, v232
	v_fma_f32 v173, v135, v236, v208
	v_lshlrev_b32_e32 v214, 16, v56
	v_and_b32_e32 v215, s100, v56
	v_lshlrev_b32_e32 v216, 16, v57
	v_and_b32_e32 v217, s100, v57
	v_add_f32_e32 v195, v214, v183
	v_add_f32_e32 v188, v215, v184
	v_add_f32_e32 v200, v216, v185
	v_add_f32_e32 v193, v217, v186
	v_fma_f32 v194, v134, v187, v195
	v_fma_f32 v207, v134, v199, v188
	v_fma_f32 v236, v134, v192, v200
	v_fma_f32 v221, v134, v245, v193
	v_fma_f32 v222, v135, v197, v194
	v_fma_f32 v223, v135, v198, v207
	v_fma_f32 v253, v135, v211, v236
	v_fma_f32 v179, v135, v240, v221
	v_lshlrev_b32_e32 v180, 16, v60
	v_and_b32_e32 v181, s100, v60
	v_lshlrev_b32_e32 v182, 16, v61
	v_and_b32_e32 v187, s100, v61
	v_add_f32_e32 v199, v180, v214
	v_add_f32_e32 v192, v181, v215
	v_add_f32_e32 v245, v182, v216
	v_add_f32_e32 v197, v187, v217
	v_fma_f32 v198, v134, v191, v199
	v_fma_f32 v211, v134, v244, v192
	v_fma_f32 v240, v134, v196, v245
	v_fma_f32 v225, v134, v189, v197
	v_fma_f32 v226, v135, v201, v198
	v_fma_f32 v227, v135, v202, v211
	v_fma_f32 v176, v135, v224, v240
	v_fma_f32 v183, v135, v249, v225
	v_lshlrev_b32_e32 v184, 16, v64
	v_and_b32_e32 v185, s100, v64
	v_lshlrev_b32_e32 v186, 16, v65
	v_and_b32_e32 v191, s100, v65
	v_add_f32_e32 v244, v184, v180
	v_add_f32_e32 v196, v185, v181
	v_add_f32_e32 v189, v186, v182
	v_add_f32_e32 v201, v191, v187
	v_fma_f32 v202, v134, v195, v244
	v_fma_f32 v224, v134, v188, v196
	v_fma_f32 v249, v134, v200, v189
	v_fma_f32 v229, v134, v193, v201
	v_fma_f32 v230, v135, v246, v202
	v_fma_f32 v231, v135, v247, v224
	v_fma_f32 v1, v135, v228, v249
	v_fma_f32 v214, v135, v204, v229
	v_lshlrev_b32_e32 v215, 16, v68
	v_and_b32_e32 v216, s100, v68
	v_lshlrev_b32_e32 v217, 16, v69
	v_and_b32_e32 v195, s100, v69
	v_add_f32_e32 v188, v215, v184
	v_add_f32_e32 v200, v216, v185
	v_add_f32_e32 v193, v217, v186
	v_add_f32_e32 v246, v195, v191
	v_fma_f32 v247, v134, v199, v188
	v_fma_f32 v228, v134, v192, v200
	v_fma_f32 v204, v134, v245, v193
	v_fma_f32 v233, v134, v197, v246
	v_fma_f32 v234, v135, v190, v247
	v_fma_f32 v235, v135, v203, v228
	v_fma_f32 v254, v135, v232, v204
	v_fma_f32 v180, v135, v208, v233
	v_fma_f32 v181, v136, v237, v234
	v_fma_f32 v182, v136, v238, v235
	v_fma_f32 v187, v136, v239, v254
	v_fma_f32 v199, v136, v177, v180
	s_add_i32 s101, s99, 1
	v_min_u32_e32 v192, s101, v137
	v_cvt_f32_u32_e32 v192, v192
	v_rcp_f32_e32 v192, v192
	s_nop 0
	v_fma_f32 v181, v181, v192, -v215
	v_fma_f32 v182, v182, v192, -v216
	v_fma_f32 v187, v187, v192, -v217
	v_fma_f32 v199, v199, v192, -v195
	v_cvt_pk_bf16_f32 v68, v181, v182
	v_cvt_pk_bf16_f32 v69, v187, v199
	v_lshlrev_b32_e32 v245, 16, v72
	v_and_b32_e32 v197, s100, v72
	v_lshlrev_b32_e32 v190, 16, v73
	v_and_b32_e32 v203, s100, v73
	v_add_f32_e32 v232, v245, v215
	v_add_f32_e32 v208, v197, v216
	v_add_f32_e32 v237, v190, v217
	v_add_f32_e32 v238, v203, v195
	v_fma_f32 v239, v134, v244, v232
	v_fma_f32 v177, v134, v196, v208
	v_fma_f32 v181, v134, v189, v237
	v_fma_f32 v182, v134, v201, v238
	v_fma_f32 v187, v135, v194, v239
	v_fma_f32 v199, v135, v207, v177
; __device__ __forceinline__ unsigned pk2(float lo, float hi) { return pg8::cvt_pk_bf16(lo, hi); }
; __global__ void __launch_bounds__(NTHR, 2) hybrid_fwd(Args args) {
;     ...
;             float a[8];
; #pragma unroll
;             for (int e = 0; e < 8; ++e) a[e] = 0.f;
;             const u32x4 u0 = qv[0];
; #pragma unroll
;             for (int j = 0; j < 16; ++j) { const float mk = j < cnt ? 1.0f : 0.0f; const u32x4 q = qv[j];
;                 a[0] += mk * bflo(q.x); a[1] += mk * bfhi(q.x); a[2] += mk * bflo(q.y); a[3] += mk * bfhi(q.y); a[4] += mk * bflo(q.z); a[5] += mk * bfhi(q.z); a[6] += mk * bflo(q.w); a[7] += mk * bfhi(q.w); }
;             const float ic = 1.0f / (float)cnt;
;             u32x4 o; o.x = pk2(a[0] * ic - bflo(u0.x), a[1] * ic - bfhi(u0.x)); o.y = pk2(a[2] * ic - bflo(u0.y), a[3] * ic - bfhi(u0.y));
;             o.z = pk2(a[4] * ic - bflo(u0.z), a[5] * ic - bfhi(u0.z)); o.w = pk2(a[6] * ic - bflo(u0.w), a[7] * ic - bfhi(u0.w));
	v_fma_f32 v192, v135, v236, v181
	v_fma_f32 v184, v135, v221, v182
	v_fma_f32 v185, v136, v241, v187
	v_fma_f32 v186, v136, v242, v199
	v_fma_f32 v191, v136, v243, v192
	v_fma_f32 v244, v136, v172, v184
	s_add_i32 s101, s99, 2
	v_min_u32_e32 v196, s101, v137
	v_cvt_f32_u32_e32 v196, v196
	v_rcp_f32_e32 v196, v196
	s_nop 0
	v_fma_f32 v185, v185, v196, -v245
	v_fma_f32 v186, v186, v196, -v197
	v_fma_f32 v191, v191, v196, -v190
	v_fma_f32 v244, v244, v196, -v203
	v_cvt_pk_bf16_f32 v72, v185, v186
	v_cvt_pk_bf16_f32 v73, v191, v244
	v_lshlrev_b32_e32 v189, 16, v76
	v_and_b32_e32 v201, s100, v76
	v_lshlrev_b32_e32 v194, 16, v77
	v_and_b32_e32 v207, s100, v77
	v_add_f32_e32 v236, v189, v245
	v_add_f32_e32 v221, v201, v197
	v_add_f32_e32 v241, v194, v190
	v_add_f32_e32 v242, v207, v203
	v_fma_f32 v243, v134, v188, v236
	v_fma_f32 v172, v134, v200, v221
	v_fma_f32 v185, v134, v193, v241
	v_fma_f32 v186, v134, v246, v242
	v_fma_f32 v191, v135, v198, v243
	v_fma_f32 v244, v135, v211, v172
	v_fma_f32 v196, v135, v240, v185
	v_fma_f32 v215, v135, v225, v186
	v_fma_f32 v216, v136, v250, v191
	v_fma_f32 v217, v136, v251, v244
	v_fma_f32 v195, v136, v252, v196
	v_fma_f32 v188, v136, v255, v215
	s_add_i32 s101, s99, 3
	v_min_u32_e32 v200, s101, v137
	v_cvt_f32_u32_e32 v200, v200
	v_rcp_f32_e32 v200, v200
	s_nop 0
	v_fma_f32 v216, v216, v200, -v189
	v_fma_f32 v217, v217, v200, -v201
	v_fma_f32 v195, v195, v200, -v194
	v_fma_f32 v188, v188, v200, -v207
	v_cvt_pk_bf16_f32 v76, v216, v217
	v_cvt_pk_bf16_f32 v77, v195, v188
	v_lshlrev_b32_e32 v193, 16, v80
	v_and_b32_e32 v246, s100, v80
	v_lshlrev_b32_e32 v198, 16, v81
	v_and_b32_e32 v211, s100, v81
	v_add_f32_e32 v240, v193, v189
	v_add_f32_e32 v225, v246, v201
	v_add_f32_e32 v250, v198, v194
	v_add_f32_e32 v251, v211, v207
	v_fma_f32 v252, v134, v232, v240
	v_fma_f32 v255, v134, v208, v225
	v_fma_f32 v216, v134, v237, v250
	v_fma_f32 v217, v134, v238, v251
	v_fma_f32 v195, v135, v202, v252
	v_fma_f32 v188, v135, v224, v255
	v_fma_f32 v200, v135, v249, v216
	v_fma_f32 v245, v135, v229, v217
	v_fma_f32 v197, v136, v205, v195
	v_fma_f32 v190, v136, v206, v188
	v_fma_f32 v203, v136, v175, v200
	v_fma_f32 v232, v136, v178, v245
	s_add_i32 s101, s99, 4
	v_min_u32_e32 v208, s101, v137
	v_cvt_f32_u32_e32 v208, v208
	v_rcp_f32_e32 v208, v208
	s_nop 0
	v_fma_f32 v197, v197, v208, -v193
	v_fma_f32 v190, v190, v208, -v246
	v_fma_f32 v203, v203, v208, -v198
	v_fma_f32 v232, v232, v208, -v211
	v_cvt_pk_bf16_f32 v80, v197, v190
	v_cvt_pk_bf16_f32 v81, v203, v232
	v_lshlrev_b32_e32 v237, 16, v84
	v_and_b32_e32 v238, s100, v84
	v_lshlrev_b32_e32 v202, 16, v85
	v_and_b32_e32 v224, s100, v85
	v_add_f32_e32 v249, v237, v193
	v_add_f32_e32 v229, v238, v246
	v_add_f32_e32 v205, v202, v198
	v_add_f32_e32 v206, v224, v211
	v_fma_f32 v175, v134, v236, v249
	v_fma_f32 v178, v134, v221, v229
	v_fma_f32 v197, v134, v241, v205
	v_fma_f32 v190, v134, v242, v206
	v_fma_f32 v203, v135, v247, v175
	v_fma_f32 v232, v135, v228, v178
	v_fma_f32 v208, v135, v204, v197
	v_fma_f32 v189, v135, v233, v190
	v_fma_f32 v201, v136, v209, v203
	v_fma_f32 v194, v136, v210, v232
	v_fma_f32 v207, v136, v0, v208
	v_fma_f32 v236, v136, v173, v189
	s_add_i32 s101, s99, 5
	v_min_u32_e32 v221, s101, v137
	v_cvt_f32_u32_e32 v221, v221
	v_rcp_f32_e32 v221, v221
	s_nop 0
	v_fma_f32 v201, v201, v221, -v237
	v_fma_f32 v194, v194, v221, -v238
	v_fma_f32 v207, v207, v221, -v202
	v_fma_f32 v236, v236, v221, -v224
	v_cvt_pk_bf16_f32 v84, v201, v194
	v_cvt_pk_bf16_f32 v85, v207, v236
	v_lshlrev_b32_e32 v241, 16, v88
	v_and_b32_e32 v242, s100, v88
	v_lshlrev_b32_e32 v247, 16, v89
	v_and_b32_e32 v228, s100, v89
	v_add_f32_e32 v204, v241, v237
	v_add_f32_e32 v233, v242, v238
	v_add_f32_e32 v209, v247, v202
	v_add_f32_e32 v210, v228, v224
	v_fma_f32 v0, v134, v240, v204
	v_fma_f32 v173, v134, v225, v233
	v_fma_f32 v201, v134, v250, v209
	v_fma_f32 v194, v134, v251, v210
	v_fma_f32 v207, v135, v239, v0
	v_fma_f32 v236, v135, v177, v173
	v_fma_f32 v221, v135, v181, v201
	v_fma_f32 v193, v135, v182, v194
	v_fma_f32 v246, v136, v222, v207
	v_fma_f32 v198, v136, v223, v236
	v_fma_f32 v211, v136, v253, v221
	v_fma_f32 v240, v136, v179, v193
	s_add_i32 s101, s99, 6
	v_min_u32_e32 v225, s101, v137
	v_cvt_f32_u32_e32 v225, v225
	v_rcp_f32_e32 v225, v225
	s_nop 0
	v_fma_f32 v246, v246, v225, -v241
	v_fma_f32 v198, v198, v225, -v242
	v_fma_f32 v211, v211, v225, -v247
	v_fma_f32 v240, v240, v225, -v228
	v_cvt_pk_bf16_f32 v88, v246, v198
	v_cvt_pk_bf16_f32 v89, v211, v240
	v_lshlrev_b32_e32 v250, 16, v92
	v_and_b32_e32 v251, s100, v92
	v_lshlrev_b32_e32 v239, 16, v93
	v_and_b32_e32 v177, s100, v93
	v_add_f32_e32 v181, v250, v241
	v_add_f32_e32 v182, v251, v242
	v_add_f32_e32 v222, v239, v247
	v_add_f32_e32 v223, v177, v228
	v_fma_f32 v253, v134, v249, v181
	v_fma_f32 v179, v134, v229, v182
	v_fma_f32 v246, v134, v205, v222
	v_fma_f32 v198, v134, v206, v223
	v_fma_f32 v211, v135, v243, v253
	v_fma_f32 v240, v135, v172, v179
	v_fma_f32 v225, v135, v185, v246
	v_fma_f32 v237, v135, v186, v198
	v_fma_f32 v238, v136, v226, v211
	v_fma_f32 v202, v136, v227, v240
	v_fma_f32 v224, v136, v176, v225
	v_fma_f32 v249, v136, v183, v237
	s_add_i32 s101, s99, 7
	v_min_u32_e32 v229, s101, v137
	v_cvt_f32_u32_e32 v229, v229
	v_rcp_f32_e32 v229, v229
	s_nop 0
	v_fma_f32 v238, v238, v229, -v250
	v_fma_f32 v202, v202, v229, -v251
	v_fma_f32 v224, v224, v229, -v239
	v_fma_f32 v249, v249, v229, -v177
	v_cvt_pk_bf16_f32 v92, v238, v202
	v_cvt_pk_bf16_f32 v93, v224, v249
	v_lshlrev_b32_e32 v205, 16, v96
	v_and_b32_e32 v206, s100, v96
	v_lshlrev_b32_e32 v243, 16, v97
	v_and_b32_e32 v172, s100, v97
; __device__ __forceinline__ unsigned pk2(float lo, float hi) { return pg8::cvt_pk_bf16(lo, hi); }
; __global__ void __launch_bounds__(NTHR, 2) hybrid_fwd(Args args) {
;     ...
;             float a[8];
; #pragma unroll
;             for (int e = 0; e < 8; ++e) a[e] = 0.f;
;             const u32x4 u0 = qv[0];
; #pragma unroll
;             for (int j = 0; j < 16; ++j) { const float mk = j < cnt ? 1.0f : 0.0f; const u32x4 q = qv[j];
;                 a[0] += mk * bflo(q.x); a[1] += mk * bfhi(q.x); a[2] += mk * bflo(q.y); a[3] += mk * bfhi(q.y); a[4] += mk * bflo(q.z); a[5] += mk * bfhi(q.z); a[6] += mk * bflo(q.w); a[7] += mk * bfhi(q.w); }
;             const float ic = 1.0f / (float)cnt;
;             u32x4 o; o.x = pk2(a[0] * ic - bflo(u0.x), a[1] * ic - bfhi(u0.x)); o.y = pk2(a[2] * ic - bflo(u0.y), a[3] * ic - bfhi(u0.y));
;             o.z = pk2(a[4] * ic - bflo(u0.z), a[5] * ic - bfhi(u0.z)); o.w = pk2(a[6] * ic - bflo(u0.w), a[7] * ic - bfhi(u0.w));
	v_add_f32_e32 v185, v205, v250
	v_add_f32_e32 v186, v206, v251
	v_add_f32_e32 v226, v243, v239
	v_add_f32_e32 v227, v172, v177
	v_fma_f32 v176, v134, v204, v185
	v_fma_f32 v183, v134, v233, v186
	v_fma_f32 v238, v134, v209, v226
	v_fma_f32 v202, v134, v210, v227
	v_fma_f32 v224, v135, v252, v176
	v_fma_f32 v249, v135, v255, v183
	v_fma_f32 v229, v135, v216, v238
	v_fma_f32 v241, v135, v217, v202
	v_fma_f32 v242, v136, v230, v224
	v_fma_f32 v247, v136, v231, v249
	v_fma_f32 v228, v136, v1, v229
	v_fma_f32 v204, v136, v214, v241
	s_add_i32 s101, s99, 8
	v_min_u32_e32 v233, s101, v137
	v_cvt_f32_u32_e32 v233, v233
	v_rcp_f32_e32 v233, v233
	s_nop 0
	v_fma_f32 v242, v242, v233, -v205
	v_fma_f32 v247, v247, v233, -v206
	v_fma_f32 v228, v228, v233, -v243
	v_fma_f32 v204, v204, v233, -v172
	v_cvt_pk_bf16_f32 v96, v242, v247
	v_cvt_pk_bf16_f32 v97, v228, v204
	v_lshlrev_b32_e32 v209, 16, v100
	v_and_b32_e32 v210, s100, v100
	v_lshlrev_b32_e32 v252, 16, v101
	v_and_b32_e32 v255, s100, v101
	v_add_f32_e32 v216, v209, v205
	v_add_f32_e32 v217, v210, v206
	v_add_f32_e32 v230, v252, v243
	v_add_f32_e32 v231, v255, v172
	v_fma_f32 v1, v134, v181, v216
	v_fma_f32 v214, v134, v182, v217
	v_fma_f32 v242, v134, v222, v230
	v_fma_f32 v247, v134, v223, v231
	v_fma_f32 v228, v135, v175, v1
	v_fma_f32 v204, v135, v178, v214
	v_fma_f32 v233, v135, v197, v242
	v_fma_f32 v250, v135, v190, v247
	v_fma_f32 v251, v136, v234, v228
	v_fma_f32 v239, v136, v235, v204
	v_fma_f32 v177, v136, v254, v233
	v_fma_f32 v181, v136, v180, v250
	s_add_i32 s101, s99, 9
	v_min_u32_e32 v182, s101, v137
	v_cvt_f32_u32_e32 v182, v182
	v_rcp_f32_e32 v182, v182
	s_nop 0
	v_fma_f32 v251, v251, v182, -v209
	v_fma_f32 v239, v239, v182, -v210
	v_fma_f32 v177, v177, v182, -v252
	v_fma_f32 v181, v181, v182, -v255
	v_cvt_pk_bf16_f32 v100, v251, v239
	v_cvt_pk_bf16_f32 v101, v177, v181
	v_lshlrev_b32_e32 v222, 16, v104
	v_and_b32_e32 v223, s100, v104
	v_lshlrev_b32_e32 v175, 16, v105
	v_and_b32_e32 v178, s100, v105
	v_add_f32_e32 v197, v222, v209
	v_add_f32_e32 v190, v223, v210
	v_add_f32_e32 v234, v175, v252
	v_add_f32_e32 v235, v178, v255
	v_fma_f32 v254, v134, v185, v197
	v_fma_f32 v180, v134, v186, v190
	v_fma_f32 v251, v134, v226, v234
	v_fma_f32 v239, v134, v227, v235
	v_fma_f32 v177, v135, v0, v254
	v_fma_f32 v181, v135, v173, v180
	v_fma_f32 v182, v135, v201, v251
	v_fma_f32 v205, v135, v194, v239
	v_fma_f32 v206, v136, v187, v177
	v_fma_f32 v243, v136, v199, v181
	v_fma_f32 v172, v136, v192, v182
	v_fma_f32 v185, v136, v184, v205
	s_add_i32 s101, s99, 10
	v_min_u32_e32 v186, s101, v137
	v_cvt_f32_u32_e32 v186, v186
	v_rcp_f32_e32 v186, v186
	s_nop 0
	v_fma_f32 v206, v206, v186, -v222
	v_fma_f32 v243, v243, v186, -v223
	v_fma_f32 v172, v172, v186, -v175
	v_fma_f32 v185, v185, v186, -v178
	v_cvt_pk_bf16_f32 v104, v206, v243
	v_cvt_pk_bf16_f32 v105, v172, v185
	v_lshlrev_b32_e32 v226, 16, v108
	v_and_b32_e32 v227, s100, v108
	v_lshlrev_b32_e32 v0, 16, v109
	v_and_b32_e32 v173, s100, v109
	v_add_f32_e32 v201, v226, v222
	v_add_f32_e32 v194, v227, v223
	v_add_f32_e32 v187, v0, v175
	v_add_f32_e32 v199, v173, v178
	v_fma_f32 v192, v134, v216, v201
	v_fma_f32 v184, v134, v217, v194
	v_fma_f32 v206, v134, v230, v187
	v_fma_f32 v243, v134, v231, v199
	v_fma_f32 v172, v135, v253, v192
	v_fma_f32 v185, v135, v179, v184
	v_fma_f32 v186, v135, v246, v206
	v_fma_f32 v209, v135, v198, v243
	v_fma_f32 v210, v136, v191, v172
	v_fma_f32 v252, v136, v244, v185
	v_fma_f32 v255, v136, v196, v186
	v_fma_f32 v216, v136, v215, v209
	s_add_i32 s101, s99, 11
	v_min_u32_e32 v217, s101, v137
	v_cvt_f32_u32_e32 v217, v217
	v_rcp_f32_e32 v217, v217
	s_nop 0
	v_fma_f32 v210, v210, v217, -v226
	v_fma_f32 v252, v252, v217, -v227
	v_fma_f32 v255, v255, v217, -v0
	v_fma_f32 v216, v216, v217, -v173
	v_cvt_pk_bf16_f32 v108, v210, v252
	v_cvt_pk_bf16_f32 v109, v255, v216
	v_lshlrev_b32_e32 v230, 16, v112
	v_and_b32_e32 v231, s100, v112
	v_lshlrev_b32_e32 v253, 16, v113
	v_and_b32_e32 v179, s100, v113
	v_add_f32_e32 v246, v230, v226
	v_add_f32_e32 v198, v231, v227
	v_add_f32_e32 v191, v253, v0
	v_add_f32_e32 v244, v179, v173
	v_fma_f32 v196, v134, v197, v246
	v_fma_f32 v215, v134, v190, v198
	v_fma_f32 v210, v134, v234, v191
	v_fma_f32 v252, v134, v235, v244
	v_fma_f32 v255, v135, v176, v196
	v_fma_f32 v216, v135, v183, v215
	v_fma_f32 v217, v135, v238, v210
	v_fma_f32 v222, v135, v202, v252
	v_fma_f32 v223, v136, v195, v255
	v_fma_f32 v175, v136, v188, v216
	v_fma_f32 v178, v136, v200, v217
	v_fma_f32 v197, v136, v245, v222
	s_add_i32 s101, s99, 12
	v_min_u32_e32 v190, s101, v137
	v_cvt_f32_u32_e32 v190, v190
	v_rcp_f32_e32 v190, v190
	s_nop 0
	v_fma_f32 v223, v223, v190, -v230
	v_fma_f32 v175, v175, v190, -v231
	v_fma_f32 v178, v178, v190, -v253
	v_fma_f32 v197, v197, v190, -v179
	v_cvt_pk_bf16_f32 v112, v223, v175
	v_cvt_pk_bf16_f32 v113, v178, v197
	v_lshlrev_b32_e32 v234, 16, v116
	v_and_b32_e32 v235, s100, v116
	v_lshlrev_b32_e32 v176, 16, v117
	v_and_b32_e32 v183, s100, v117
	v_add_f32_e32 v238, v234, v230
	v_add_f32_e32 v202, v235, v231
	v_add_f32_e32 v195, v176, v253
	v_add_f32_e32 v188, v183, v179
	v_fma_f32 v200, v134, v201, v238
	v_fma_f32 v245, v134, v194, v202
	v_fma_f32 v223, v134, v187, v195
	v_fma_f32 v175, v134, v199, v188
	v_fma_f32 v178, v135, v1, v200
	v_fma_f32 v197, v135, v214, v245
	v_fma_f32 v190, v135, v242, v223
	v_fma_f32 v226, v135, v247, v175
	v_fma_f32 v227, v136, v203, v178
	v_fma_f32 v0, v136, v232, v197
	v_fma_f32 v173, v136, v208, v190
	v_fma_f32 v201, v136, v189, v226
	s_add_i32 s101, s99, 13
	v_min_u32_e32 v194, s101, v137
	v_cvt_f32_u32_e32 v194, v194
	v_rcp_f32_e32 v194, v194
	s_nop 0
; __device__ __forceinline__ unsigned pk2(float lo, float hi) { return pg8::cvt_pk_bf16(lo, hi); }
; __global__ void __launch_bounds__(NTHR, 2) hybrid_fwd(Args args) {
;     ...
;             float a[8];
; #pragma unroll
;             for (int e = 0; e < 8; ++e) a[e] = 0.f;
;             const u32x4 u0 = qv[0];
; #pragma unroll
;             for (int j = 0; j < 16; ++j) { const float mk = j < cnt ? 1.0f : 0.0f; const u32x4 q = qv[j];
;                 a[0] += mk * bflo(q.x); a[1] += mk * bfhi(q.x); a[2] += mk * bflo(q.y); a[3] += mk * bfhi(q.y); a[4] += mk * bflo(q.z); a[5] += mk * bfhi(q.z); a[6] += mk * bflo(q.w); a[7] += mk * bfhi(q.w); }
;             const float ic = 1.0f / (float)cnt;
;             u32x4 o; o.x = pk2(a[0] * ic - bflo(u0.x), a[1] * ic - bfhi(u0.x)); o.y = pk2(a[2] * ic - bflo(u0.y), a[3] * ic - bfhi(u0.y));
;             o.z = pk2(a[4] * ic - bflo(u0.z), a[5] * ic - bfhi(u0.z)); o.w = pk2(a[6] * ic - bflo(u0.w), a[7] * ic - bfhi(u0.w));
;             *(u32x4*)(AD + (size_t)t * 1024 + lane * 8) = o; }
	v_fma_f32 v227, v227, v194, -v234
	v_fma_f32 v0, v0, v194, -v235
	v_fma_f32 v173, v173, v194, -v176
	v_fma_f32 v201, v201, v194, -v183
	v_cvt_pk_bf16_f32 v116, v227, v0
	v_cvt_pk_bf16_f32 v117, v173, v201
	v_lshlrev_b32_e32 v187, 16, v120
	v_and_b32_e32 v199, s100, v120
	v_lshlrev_b32_e32 v1, 16, v121
	v_and_b32_e32 v214, s100, v121
	v_add_f32_e32 v242, v187, v234
	v_add_f32_e32 v247, v199, v235
	v_add_f32_e32 v203, v1, v176
	v_add_f32_e32 v232, v214, v183
	v_fma_f32 v208, v134, v246, v242
	v_fma_f32 v189, v134, v198, v247
	v_fma_f32 v227, v134, v191, v203
	v_fma_f32 v0, v134, v244, v232
	v_fma_f32 v173, v135, v254, v208
	v_fma_f32 v201, v135, v180, v189
	v_fma_f32 v194, v135, v251, v227
	v_fma_f32 v230, v135, v239, v0
	v_fma_f32 v231, v136, v207, v173
	v_fma_f32 v253, v136, v236, v201
	v_fma_f32 v179, v136, v221, v194
	v_fma_f32 v246, v136, v193, v230
	s_add_i32 s101, s99, 14
	v_min_u32_e32 v198, s101, v137
	v_cvt_f32_u32_e32 v198, v198
	v_rcp_f32_e32 v198, v198
	s_nop 0
	v_fma_f32 v231, v231, v198, -v187
	v_fma_f32 v253, v253, v198, -v199
	v_fma_f32 v179, v179, v198, -v1
	v_fma_f32 v246, v246, v198, -v214
	v_cvt_pk_bf16_f32 v120, v231, v253
	v_cvt_pk_bf16_f32 v121, v179, v246
	v_lshlrev_b32_e32 v191, 16, v124
	v_and_b32_e32 v244, s100, v124
	v_lshlrev_b32_e32 v254, 16, v125
	v_and_b32_e32 v180, s100, v125
	v_add_f32_e32 v251, v191, v187
	v_add_f32_e32 v239, v244, v199
	v_add_f32_e32 v207, v254, v1
	v_add_f32_e32 v236, v180, v214
	v_fma_f32 v221, v134, v238, v251
	v_fma_f32 v193, v134, v202, v239
	v_fma_f32 v231, v134, v195, v207
	v_fma_f32 v253, v134, v188, v236
	v_fma_f32 v179, v135, v192, v221
	v_fma_f32 v246, v135, v184, v193
	v_fma_f32 v198, v135, v206, v231
	v_fma_f32 v234, v135, v243, v253
	v_fma_f32 v235, v136, v211, v179
	v_fma_f32 v176, v136, v240, v246
	v_fma_f32 v183, v136, v225, v198
	v_fma_f32 v238, v136, v237, v234
	s_add_i32 s101, s99, 15
	v_min_u32_e32 v202, s101, v137
	v_cvt_f32_u32_e32 v202, v202
	v_rcp_f32_e32 v202, v202
	s_nop 0
	v_fma_f32 v235, v235, v202, -v191
	v_fma_f32 v176, v176, v202, -v244
	v_fma_f32 v183, v183, v202, -v254
	v_fma_f32 v238, v238, v202, -v180
	v_cvt_pk_bf16_f32 v124, v235, v176
	v_cvt_pk_bf16_f32 v125, v183, v238
	v_lshlrev_b32_e32 v195, 16, v128
	v_and_b32_e32 v188, s100, v128
	v_lshlrev_b32_e32 v192, 16, v129
	v_and_b32_e32 v184, s100, v129
	v_add_f32_e32 v206, v195, v191
	v_add_f32_e32 v243, v188, v244
	v_add_f32_e32 v211, v192, v254
	v_add_f32_e32 v240, v184, v180
	v_fma_f32 v225, v134, v242, v206
	v_fma_f32 v237, v134, v247, v243
	v_fma_f32 v235, v134, v203, v211
	v_fma_f32 v176, v134, v232, v240
	v_fma_f32 v183, v135, v196, v225
	v_fma_f32 v238, v135, v215, v237
	v_fma_f32 v202, v135, v210, v235
	v_fma_f32 v187, v135, v252, v176
	v_fma_f32 v199, v136, v224, v183
	v_fma_f32 v1, v136, v249, v238
	v_fma_f32 v214, v136, v229, v202
	v_fma_f32 v242, v136, v241, v187
	s_add_i32 s101, s99, 16
	v_min_u32_e32 v247, s101, v137
	v_cvt_f32_u32_e32 v247, v247
	v_rcp_f32_e32 v247, v247
	s_nop 0
	v_fma_f32 v199, v199, v247, -v195
	v_fma_f32 v1, v1, v247, -v188
	v_fma_f32 v214, v214, v247, -v192
	v_fma_f32 v242, v242, v247, -v184
	v_cvt_pk_bf16_f32 v128, v199, v1
	v_cvt_pk_bf16_f32 v129, v214, v242
	v_mov_b32_e32 v175, 0
	v_mov_b32_e32 v176, 0
	v_mov_b32_e32 v177, 0
	v_mov_b32_e32 v178, 0
	v_mov_b32_e32 v179, 0
	v_mov_b32_e32 v180, 0
	v_mov_b32_e32 v181, 0
	v_mov_b32_e32 v182, 0
	v_mov_b32_e32 v183, 0
	v_mov_b32_e32 v184, 0
	v_mov_b32_e32 v185, 0
	v_mov_b32_e32 v186, 0
	v_mov_b32_e32 v187, 0
	v_mov_b32_e32 v188, 0
	v_mov_b32_e32 v189, 0
	v_mov_b32_e32 v190, 0
	v_mov_b32_e32 v191, 0
	v_mov_b32_e32 v192, 0
	v_mov_b32_e32 v193, 0
	v_mov_b32_e32 v194, 0
	v_mov_b32_e32 v195, 0
	v_mov_b32_e32 v196, 0
	v_mov_b32_e32 v197, 0
	v_mov_b32_e32 v198, 0
	v_mov_b32_e32 v199, 0
	v_mov_b32_e32 v200, 0
	v_mov_b32_e32 v201, 0
	v_mov_b32_e32 v202, 0
	v_mov_b32_e32 v203, 0
	v_mov_b32_e32 v204, 0
	v_mov_b32_e32 v205, 0
	v_mov_b32_e32 v206, 0
	v_mov_b32_e32 v207, 0
	v_mov_b32_e32 v208, 0
	v_mov_b32_e32 v209, 0
	v_mov_b32_e32 v210, 0
	v_mov_b32_e32 v211, 0
	v_mov_b32_e32 v221, 0
	v_mov_b32_e32 v222, 0
	v_mov_b32_e32 v223, 0
	v_mov_b32_e32 v224, 0
	v_mov_b32_e32 v225, 0
	v_mov_b32_e32 v226, 0
	v_mov_b32_e32 v227, 0
	v_mov_b32_e32 v228, 0
	v_mov_b32_e32 v229, 0
	v_mov_b32_e32 v230, 0
	v_mov_b32_e32 v231, 0
	v_mov_b32_e32 v232, 0
	v_mov_b32_e32 v233, 0
	v_mov_b32_e32 v234, 0
	v_mov_b32_e32 v235, 0
	v_mov_b32_e32 v236, 0
	v_mov_b32_e32 v237, 0
	v_mov_b32_e32 v238, 0
	v_mov_b32_e32 v239, 0
	v_mov_b32_e32 v240, 0
	v_mov_b32_e32 v241, 0
	v_mov_b32_e32 v242, 0
	v_mov_b32_e32 v243, 0
	v_lshlrev_b32_e32 v0, 16, v10
	v_and_b32_e32 v1, s100, v10
	v_lshlrev_b32_e32 v172, 16, v11
	v_and_b32_e32 v173, s100, v11
	v_add_f32_e32 v214, v0, v175
	v_add_f32_e32 v215, v1, v176
	v_add_f32_e32 v216, v172, v177
	v_add_f32_e32 v217, v173, v178
	v_fma_f32 v244, v134, v179, v214
	v_fma_f32 v245, v134, v180, v215
	v_fma_f32 v246, v134, v181, v216
	v_fma_f32 v247, v134, v182, v217
	v_fma_f32 v249, v135, v187, v244
	v_fma_f32 v250, v135, v188, v245
	v_fma_f32 v251, v135, v189, v246
	v_fma_f32 v252, v135, v190, v247
	v_lshlrev_b32_e32 v253, 16, v14
	v_and_b32_e32 v254, s100, v14
	v_lshlrev_b32_e32 v255, 16, v15
	v_and_b32_e32 v179, s100, v15
	v_add_f32_e32 v180, v253, v0
	v_add_f32_e32 v181, v254, v1
	v_add_f32_e32 v182, v255, v172
	v_add_f32_e32 v187, v179, v173
	v_fma_f32 v188, v134, v183, v180
	v_fma_f32 v189, v134, v184, v181
	v_fma_f32 v190, v134, v185, v182
	v_fma_f32 v203, v134, v186, v187
	v_fma_f32 v204, v135, v191, v188
	v_fma_f32 v205, v135, v192, v189
	v_fma_f32 v206, v135, v193, v190
	v_fma_f32 v175, v135, v194, v203
	v_lshlrev_b32_e32 v176, 16, v18
; __device__ __forceinline__ unsigned pk2(float lo, float hi) { return pg8::cvt_pk_bf16(lo, hi); }
; __global__ void __launch_bounds__(NTHR, 2) hybrid_fwd(Args args) {
;     ...
;         for (int i = 0; i < nr; ++i) { const int t = t_b + i;
;             const int sp = t & 2047, cnt = (sp + 1) < w ? (sp + 1) : w;
;             u32x4 qv[16];
; #pragma unroll
;             for (int j = 0; j < 16; ++j) qv[j] = qn[j];
;             if (i + 1 < nr) { const int t1 = t + 1, sp1 = t1 & 2047, c1_ = (sp1 + 1) < w ? (sp1 + 1) : w;
; #pragma unroll
;                 for (int j = 0; j < 16; ++j) qn[j] = *(const u32x4*)(UB + (size_t)(j < c1_ ? t1 - j : t1) * 512 + lane * 8); }
;             float a[8];
; #pragma unroll
;             for (int e = 0; e < 8; ++e) a[e] = 0.f;
;             const u32x4 u0 = qv[0];
; #pragma unroll
;             for (int j = 0; j < 16; ++j) { const float mk = j < cnt ? 1.0f : 0.0f; const u32x4 q = qv[j];
;                 a[0] += mk * bflo(q.x); a[1] += mk * bfhi(q.x); a[2] += mk * bflo(q.y); a[3] += mk * bfhi(q.y); a[4] += mk * bflo(q.z); a[5] += mk * bfhi(q.z); a[6] += mk * bflo(q.w); a[7] += mk * bfhi(q.w); }
;             const float ic = 1.0f / (float)cnt;
;             u32x4 o; o.x = pk2(a[0] * ic - bflo(u0.x), a[1] * ic - bfhi(u0.x)); o.y = pk2(a[2] * ic - bflo(u0.y), a[3] * ic - bfhi(u0.y));
;             o.z = pk2(a[4] * ic - bflo(u0.z), a[5] * ic - bfhi(u0.z)); o.w = pk2(a[6] * ic - bflo(u0.w), a[7] * ic - bfhi(u0.w));
;             *(u32x4*)(AD + (size_t)t * 1024 + lane * 8) = o; }
	v_and_b32_e32 v177, s100, v18
	v_lshlrev_b32_e32 v178, 16, v19
	v_and_b32_e32 v183, s100, v19
	v_add_f32_e32 v184, v176, v253
	v_add_f32_e32 v185, v177, v254
	v_add_f32_e32 v186, v178, v255
	v_add_f32_e32 v191, v183, v179
	v_fma_f32 v192, v134, v214, v184
	v_fma_f32 v193, v134, v215, v185
	v_fma_f32 v194, v134, v216, v186
	v_fma_f32 v207, v134, v217, v191
	v_fma_f32 v208, v135, v195, v192
	v_fma_f32 v209, v135, v196, v193
	v_fma_f32 v210, v135, v197, v194
	v_fma_f32 v0, v135, v198, v207
	v_lshlrev_b32_e32 v1, 16, v22
	v_and_b32_e32 v172, s100, v22
	v_lshlrev_b32_e32 v173, 16, v23
	v_and_b32_e32 v214, s100, v23
	v_add_f32_e32 v215, v1, v176
	v_add_f32_e32 v216, v172, v177
	v_add_f32_e32 v217, v173, v178
	v_add_f32_e32 v195, v214, v183
	v_fma_f32 v196, v134, v180, v215
	v_fma_f32 v197, v134, v181, v216
	v_fma_f32 v198, v134, v182, v217
	v_fma_f32 v211, v134, v187, v195
	v_fma_f32 v221, v135, v199, v196
	v_fma_f32 v222, v135, v200, v197
	v_fma_f32 v223, v135, v201, v198
	v_fma_f32 v253, v135, v202, v211
	v_lshlrev_b32_e32 v254, 16, v26
	v_and_b32_e32 v255, s100, v26
	v_lshlrev_b32_e32 v179, 16, v27
	v_and_b32_e32 v180, s100, v27
	v_add_f32_e32 v181, v254, v1
	v_add_f32_e32 v182, v255, v172
	v_add_f32_e32 v187, v179, v173
	v_add_f32_e32 v199, v180, v214
	v_fma_f32 v200, v134, v184, v181
	v_fma_f32 v201, v134, v185, v182
	v_fma_f32 v202, v134, v186, v187
	v_fma_f32 v224, v134, v191, v199
	v_fma_f32 v225, v135, v244, v200
	v_fma_f32 v226, v135, v245, v201
	v_fma_f32 v227, v135, v246, v202
	v_fma_f32 v176, v135, v247, v224
	v_lshlrev_b32_e32 v177, 16, v30
	v_and_b32_e32 v178, s100, v30
	v_lshlrev_b32_e32 v183, 16, v31
	v_and_b32_e32 v184, s100, v31
	v_add_f32_e32 v185, v177, v254
	v_add_f32_e32 v186, v178, v255
	v_add_f32_e32 v191, v183, v179
	v_add_f32_e32 v244, v184, v180
	v_fma_f32 v245, v134, v215, v185
	v_fma_f32 v246, v134, v216, v186
	v_fma_f32 v247, v134, v217, v191
	v_fma_f32 v228, v134, v195, v244
	v_fma_f32 v229, v135, v188, v245
	v_fma_f32 v230, v135, v189, v246
	v_fma_f32 v231, v135, v190, v247
	v_fma_f32 v1, v135, v203, v228
	v_lshlrev_b32_e32 v172, 16, v34
	v_and_b32_e32 v173, s100, v34
	v_lshlrev_b32_e32 v214, 16, v35
	v_and_b32_e32 v215, s100, v35
	v_add_f32_e32 v216, v172, v177
	v_add_f32_e32 v217, v173, v178
	v_add_f32_e32 v195, v214, v183
	v_add_f32_e32 v188, v215, v184
	v_fma_f32 v189, v134, v181, v216
	v_fma_f32 v190, v134, v182, v217
	v_fma_f32 v203, v134, v187, v195
	v_fma_f32 v232, v134, v199, v188
	v_fma_f32 v233, v135, v192, v189
	v_fma_f32 v234, v135, v193, v190
	v_fma_f32 v235, v135, v194, v203
	v_fma_f32 v254, v135, v207, v232
	v_lshlrev_b32_e32 v255, 16, v38
	v_and_b32_e32 v179, s100, v38
	v_lshlrev_b32_e32 v180, 16, v39
	v_and_b32_e32 v181, s100, v39
	v_add_f32_e32 v182, v255, v172
	v_add_f32_e32 v187, v179, v173
	v_add_f32_e32 v199, v180, v214
	v_add_f32_e32 v192, v181, v215
	v_fma_f32 v193, v134, v185, v182
	v_fma_f32 v194, v134, v186, v187
	v_fma_f32 v207, v134, v191, v199
	v_fma_f32 v236, v134, v244, v192
	v_fma_f32 v237, v135, v196, v193
	v_fma_f32 v238, v135, v197, v194
	v_fma_f32 v239, v135, v198, v207
	v_fma_f32 v177, v135, v211, v236
	v_lshlrev_b32_e32 v178, 16, v42
	v_and_b32_e32 v183, s100, v42
	v_lshlrev_b32_e32 v184, 16, v43
	v_and_b32_e32 v185, s100, v43
	v_add_f32_e32 v186, v178, v255
	v_add_f32_e32 v191, v183, v179
	v_add_f32_e32 v244, v184, v180
	v_add_f32_e32 v196, v185, v181
	v_fma_f32 v197, v134, v216, v186
	v_fma_f32 v198, v134, v217, v191
	v_fma_f32 v211, v134, v195, v244
	v_fma_f32 v240, v134, v188, v196
	v_fma_f32 v241, v135, v200, v197
	v_fma_f32 v242, v135, v201, v198
	v_fma_f32 v243, v135, v202, v211
	v_fma_f32 v172, v135, v224, v240
	v_lshlrev_b32_e32 v173, 16, v46
	v_and_b32_e32 v214, s100, v46
	v_lshlrev_b32_e32 v215, 16, v47
	v_and_b32_e32 v216, s100, v47
	v_add_f32_e32 v217, v173, v178
	v_add_f32_e32 v195, v214, v183
	v_add_f32_e32 v188, v215, v184
	v_add_f32_e32 v200, v216, v185
	v_fma_f32 v201, v134, v182, v217
	v_fma_f32 v202, v134, v187, v195
	v_fma_f32 v224, v134, v199, v188
	v_fma_f32 v249, v134, v192, v200
	v_fma_f32 v250, v135, v245, v201
	v_fma_f32 v251, v135, v246, v202
	v_fma_f32 v252, v135, v247, v224
	v_fma_f32 v255, v135, v228, v249
	v_lshlrev_b32_e32 v179, 16, v50
	v_and_b32_e32 v180, s100, v50
	v_lshlrev_b32_e32 v181, 16, v51
	v_and_b32_e32 v182, s100, v51
	v_add_f32_e32 v187, v179, v173
	v_add_f32_e32 v199, v180, v214
	v_add_f32_e32 v192, v181, v215
	v_add_f32_e32 v245, v182, v216
	v_fma_f32 v246, v134, v186, v187
	v_fma_f32 v247, v134, v191, v199
	v_fma_f32 v228, v134, v244, v192
	v_fma_f32 v204, v134, v196, v245
	v_fma_f32 v205, v135, v189, v246
	v_fma_f32 v206, v135, v190, v247
	v_fma_f32 v175, v135, v203, v228
	v_fma_f32 v178, v135, v232, v204
	v_lshlrev_b32_e32 v183, 16, v54
	v_and_b32_e32 v184, s100, v54
	v_lshlrev_b32_e32 v185, 16, v55
	v_and_b32_e32 v186, s100, v55
	v_add_f32_e32 v191, v183, v179
	v_add_f32_e32 v244, v184, v180
	v_add_f32_e32 v196, v185, v181
	v_add_f32_e32 v189, v186, v182
	v_fma_f32 v190, v134, v217, v191
	v_fma_f32 v203, v134, v195, v244
	v_fma_f32 v232, v134, v188, v196
	v_fma_f32 v208, v134, v200, v189
	v_fma_f32 v209, v135, v193, v190
	v_fma_f32 v210, v135, v194, v203
	v_fma_f32 v0, v135, v207, v232
	v_fma_f32 v173, v135, v236, v208
	v_lshlrev_b32_e32 v214, 16, v58
	v_and_b32_e32 v215, s100, v58
	v_lshlrev_b32_e32 v216, 16, v59
	v_and_b32_e32 v217, s100, v59
	v_add_f32_e32 v195, v214, v183
	v_add_f32_e32 v188, v215, v184
	v_add_f32_e32 v200, v216, v185
	v_add_f32_e32 v193, v217, v186
	v_fma_f32 v194, v134, v187, v195
	v_fma_f32 v207, v134, v199, v188
	v_fma_f32 v236, v134, v192, v200
	v_fma_f32 v221, v134, v245, v193
; __device__ __forceinline__ unsigned pk2(float lo, float hi) { return pg8::cvt_pk_bf16(lo, hi); }
; __global__ void __launch_bounds__(NTHR, 2) hybrid_fwd(Args args) {
;     ...
;         for (int i = 0; i < nr; ++i) { const int t = t_b + i;
;             const int sp = t & 2047, cnt = (sp + 1) < w ? (sp + 1) : w;
;             u32x4 qv[16];
; #pragma unroll
;             for (int j = 0; j < 16; ++j) qv[j] = qn[j];
;             if (i + 1 < nr) { const int t1 = t + 1, sp1 = t1 & 2047, c1_ = (sp1 + 1) < w ? (sp1 + 1) : w;
; #pragma unroll
;                 for (int j = 0; j < 16; ++j) qn[j] = *(const u32x4*)(UB + (size_t)(j < c1_ ? t1 - j : t1) * 512 + lane * 8); }
;             float a[8];
; #pragma unroll
;             for (int e = 0; e < 8; ++e) a[e] = 0.f;
;             const u32x4 u0 = qv[0];
; #pragma unroll
;             for (int j = 0; j < 16; ++j) { const float mk = j < cnt ? 1.0f : 0.0f; const u32x4 q = qv[j];
;                 a[0] += mk * bflo(q.x); a[1] += mk * bfhi(q.x); a[2] += mk * bflo(q.y); a[3] += mk * bfhi(q.y); a[4] += mk * bflo(q.z); a[5] += mk * bfhi(q.z); a[6] += mk * bflo(q.w); a[7] += mk * bfhi(q.w); }
;             const float ic = 1.0f / (float)cnt;
;             u32x4 o; o.x = pk2(a[0] * ic - bflo(u0.x), a[1] * ic - bfhi(u0.x)); o.y = pk2(a[2] * ic - bflo(u0.y), a[3] * ic - bfhi(u0.y));
;             o.z = pk2(a[4] * ic - bflo(u0.z), a[5] * ic - bfhi(u0.z)); o.w = pk2(a[6] * ic - bflo(u0.w), a[7] * ic - bfhi(u0.w));
;             *(u32x4*)(AD + (size_t)t * 1024 + lane * 8) = o; }
	v_fma_f32 v222, v135, v197, v194
	v_fma_f32 v223, v135, v198, v207
	v_fma_f32 v253, v135, v211, v236
	v_fma_f32 v179, v135, v240, v221
	v_lshlrev_b32_e32 v180, 16, v62
	v_and_b32_e32 v181, s100, v62
	v_lshlrev_b32_e32 v182, 16, v63
	v_and_b32_e32 v187, s100, v63
	v_add_f32_e32 v199, v180, v214
	v_add_f32_e32 v192, v181, v215
	v_add_f32_e32 v245, v182, v216
	v_add_f32_e32 v197, v187, v217
	v_fma_f32 v198, v134, v191, v199
	v_fma_f32 v211, v134, v244, v192
	v_fma_f32 v240, v134, v196, v245
	v_fma_f32 v225, v134, v189, v197
	v_fma_f32 v226, v135, v201, v198
	v_fma_f32 v227, v135, v202, v211
	v_fma_f32 v176, v135, v224, v240
	v_fma_f32 v183, v135, v249, v225
	v_lshlrev_b32_e32 v184, 16, v66
	v_and_b32_e32 v185, s100, v66
	v_lshlrev_b32_e32 v186, 16, v67
	v_and_b32_e32 v191, s100, v67
	v_add_f32_e32 v244, v184, v180
	v_add_f32_e32 v196, v185, v181
	v_add_f32_e32 v189, v186, v182
	v_add_f32_e32 v201, v191, v187
	v_fma_f32 v202, v134, v195, v244
	v_fma_f32 v224, v134, v188, v196
	v_fma_f32 v249, v134, v200, v189
	v_fma_f32 v229, v134, v193, v201
	v_fma_f32 v230, v135, v246, v202
	v_fma_f32 v231, v135, v247, v224
	v_fma_f32 v1, v135, v228, v249
	v_fma_f32 v214, v135, v204, v229
	v_lshlrev_b32_e32 v215, 16, v70
	v_and_b32_e32 v216, s100, v70
	v_lshlrev_b32_e32 v217, 16, v71
	v_and_b32_e32 v195, s100, v71
	v_add_f32_e32 v188, v215, v184
	v_add_f32_e32 v200, v216, v185
	v_add_f32_e32 v193, v217, v186
	v_add_f32_e32 v246, v195, v191
	v_fma_f32 v247, v134, v199, v188
	v_fma_f32 v228, v134, v192, v200
	v_fma_f32 v204, v134, v245, v193
	v_fma_f32 v233, v134, v197, v246
	v_fma_f32 v234, v135, v190, v247
	v_fma_f32 v235, v135, v203, v228
	v_fma_f32 v254, v135, v232, v204
	v_fma_f32 v180, v135, v208, v233
	v_fma_f32 v181, v136, v237, v234
	v_fma_f32 v182, v136, v238, v235
	v_fma_f32 v187, v136, v239, v254
	v_fma_f32 v199, v136, v177, v180
	s_add_i32 s101, s99, 1
	v_min_u32_e32 v192, s101, v137
	v_cvt_f32_u32_e32 v192, v192
	v_rcp_f32_e32 v192, v192
	s_nop 0
	v_fma_f32 v181, v181, v192, -v215
	v_fma_f32 v182, v182, v192, -v216
	v_fma_f32 v187, v187, v192, -v217
	v_fma_f32 v199, v199, v192, -v195
	v_cvt_pk_bf16_f32 v70, v181, v182
	v_cvt_pk_bf16_f32 v71, v187, v199
	global_store_dwordx4 v[138:139], v[68:71], off
	v_lshlrev_b32_e32 v245, 16, v74
	v_and_b32_e32 v197, s100, v74
	v_lshlrev_b32_e32 v190, 16, v75
	v_and_b32_e32 v203, s100, v75
	v_add_f32_e32 v232, v245, v215
	v_add_f32_e32 v208, v197, v216
	v_add_f32_e32 v237, v190, v217
	v_add_f32_e32 v238, v203, v195
	v_fma_f32 v239, v134, v244, v232
	v_fma_f32 v177, v134, v196, v208
	v_fma_f32 v181, v134, v189, v237
	v_fma_f32 v182, v134, v201, v238
	v_fma_f32 v187, v135, v194, v239
	v_fma_f32 v199, v135, v207, v177
	v_fma_f32 v192, v135, v236, v181
	v_fma_f32 v184, v135, v221, v182
	v_fma_f32 v185, v136, v241, v187
	v_fma_f32 v186, v136, v242, v199
	v_fma_f32 v191, v136, v243, v192
	v_fma_f32 v244, v136, v172, v184
	s_add_i32 s101, s99, 2
	v_min_u32_e32 v196, s101, v137
	v_cvt_f32_u32_e32 v196, v196
	v_rcp_f32_e32 v196, v196
	s_nop 0
	v_fma_f32 v185, v185, v196, -v245
	v_fma_f32 v186, v186, v196, -v197
	v_fma_f32 v191, v191, v196, -v190
	v_fma_f32 v244, v244, v196, -v203
	v_cvt_pk_bf16_f32 v74, v185, v186
	v_cvt_pk_bf16_f32 v75, v191, v244
	global_store_dwordx4 v[138:139], v[72:75], off offset:2048
	v_lshl_add_u64 v[138:139], v[138:139], 0, s[26:27]
	v_lshlrev_b32_e32 v189, 16, v78
	v_and_b32_e32 v201, s100, v78
	v_lshlrev_b32_e32 v194, 16, v79
	v_and_b32_e32 v207, s100, v79
	v_add_f32_e32 v236, v189, v245
	v_add_f32_e32 v221, v201, v197
	v_add_f32_e32 v241, v194, v190
	v_add_f32_e32 v242, v207, v203
	v_fma_f32 v243, v134, v188, v236
	v_fma_f32 v172, v134, v200, v221
	v_fma_f32 v185, v134, v193, v241
	v_fma_f32 v186, v134, v246, v242
	v_fma_f32 v191, v135, v198, v243
	v_fma_f32 v244, v135, v211, v172
	v_fma_f32 v196, v135, v240, v185
	v_fma_f32 v215, v135, v225, v186
	v_fma_f32 v216, v136, v250, v191
	v_fma_f32 v217, v136, v251, v244
	v_fma_f32 v195, v136, v252, v196
	v_fma_f32 v188, v136, v255, v215
	s_add_i32 s101, s99, 3
	v_min_u32_e32 v200, s101, v137
	v_cvt_f32_u32_e32 v200, v200
	v_rcp_f32_e32 v200, v200
	s_nop 0
	v_fma_f32 v216, v216, v200, -v189
	v_fma_f32 v217, v217, v200, -v201
	v_fma_f32 v195, v195, v200, -v194
	v_fma_f32 v188, v188, v200, -v207
	v_cvt_pk_bf16_f32 v78, v216, v217
	v_cvt_pk_bf16_f32 v79, v195, v188
	global_store_dwordx4 v[138:139], v[76:79], off
	v_lshlrev_b32_e32 v193, 16, v82
	v_and_b32_e32 v246, s100, v82
	v_lshlrev_b32_e32 v198, 16, v83
	v_and_b32_e32 v211, s100, v83
	v_add_f32_e32 v240, v193, v189
	v_add_f32_e32 v225, v246, v201
	v_add_f32_e32 v250, v198, v194
	v_add_f32_e32 v251, v211, v207
	v_fma_f32 v252, v134, v232, v240
	v_fma_f32 v255, v134, v208, v225
	v_fma_f32 v216, v134, v237, v250
	v_fma_f32 v217, v134, v238, v251
	v_fma_f32 v195, v135, v202, v252
	v_fma_f32 v188, v135, v224, v255
	v_fma_f32 v200, v135, v249, v216
	v_fma_f32 v245, v135, v229, v217
	v_fma_f32 v197, v136, v205, v195
	v_fma_f32 v190, v136, v206, v188
	v_fma_f32 v203, v136, v175, v200
	v_fma_f32 v232, v136, v178, v245
	s_add_i32 s101, s99, 4
	v_min_u32_e32 v208, s101, v137
	v_cvt_f32_u32_e32 v208, v208
	v_rcp_f32_e32 v208, v208
	s_nop 0
	v_fma_f32 v197, v197, v208, -v193
	v_fma_f32 v190, v190, v208, -v246
	v_fma_f32 v203, v203, v208, -v198
	v_fma_f32 v232, v232, v208, -v211
	v_cvt_pk_bf16_f32 v82, v197, v190
	v_cvt_pk_bf16_f32 v83, v203, v232
	global_store_dwordx4 v[138:139], v[80:83], off offset:2048
	v_lshl_add_u64 v[138:139], v[138:139], 0, s[26:27]
	v_lshlrev_b32_e32 v237, 16, v86
	v_and_b32_e32 v238, s100, v86
	v_lshlrev_b32_e32 v202, 16, v87
	v_and_b32_e32 v224, s100, v87
	v_add_f32_e32 v249, v237, v193
; __device__ __forceinline__ unsigned pk2(float lo, float hi) { return pg8::cvt_pk_bf16(lo, hi); }
; __global__ void __launch_bounds__(NTHR, 2) hybrid_fwd(Args args) {
;     ...
;         for (int i = 0; i < nr; ++i) { const int t = t_b + i;
;             const int sp = t & 2047, cnt = (sp + 1) < w ? (sp + 1) : w;
;             u32x4 qv[16];
; #pragma unroll
;             for (int j = 0; j < 16; ++j) qv[j] = qn[j];
;             if (i + 1 < nr) { const int t1 = t + 1, sp1 = t1 & 2047, c1_ = (sp1 + 1) < w ? (sp1 + 1) : w;
; #pragma unroll
;                 for (int j = 0; j < 16; ++j) qn[j] = *(const u32x4*)(UB + (size_t)(j < c1_ ? t1 - j : t1) * 512 + lane * 8); }
;             float a[8];
; #pragma unroll
;             for (int e = 0; e < 8; ++e) a[e] = 0.f;
;             const u32x4 u0 = qv[0];
; #pragma unroll
;             for (int j = 0; j < 16; ++j) { const float mk = j < cnt ? 1.0f : 0.0f; const u32x4 q = qv[j];
;                 a[0] += mk * bflo(q.x); a[1] += mk * bfhi(q.x); a[2] += mk * bflo(q.y); a[3] += mk * bfhi(q.y); a[4] += mk * bflo(q.z); a[5] += mk * bfhi(q.z); a[6] += mk * bflo(q.w); a[7] += mk * bfhi(q.w); }
;             const float ic = 1.0f / (float)cnt;
;             u32x4 o; o.x = pk2(a[0] * ic - bflo(u0.x), a[1] * ic - bfhi(u0.x)); o.y = pk2(a[2] * ic - bflo(u0.y), a[3] * ic - bfhi(u0.y));
;             o.z = pk2(a[4] * ic - bflo(u0.z), a[5] * ic - bfhi(u0.z)); o.w = pk2(a[6] * ic - bflo(u0.w), a[7] * ic - bfhi(u0.w));
;             *(u32x4*)(AD + (size_t)t * 1024 + lane * 8) = o; }
	v_add_f32_e32 v229, v238, v246
	v_add_f32_e32 v205, v202, v198
	v_add_f32_e32 v206, v224, v211
	v_fma_f32 v175, v134, v236, v249
	v_fma_f32 v178, v134, v221, v229
	v_fma_f32 v197, v134, v241, v205
	v_fma_f32 v190, v134, v242, v206
	v_fma_f32 v203, v135, v247, v175
	v_fma_f32 v232, v135, v228, v178
	v_fma_f32 v208, v135, v204, v197
	v_fma_f32 v189, v135, v233, v190
	v_fma_f32 v201, v136, v209, v203
	v_fma_f32 v194, v136, v210, v232
	v_fma_f32 v207, v136, v0, v208
	v_fma_f32 v236, v136, v173, v189
	s_add_i32 s101, s99, 5
	v_min_u32_e32 v221, s101, v137
	v_cvt_f32_u32_e32 v221, v221
	v_rcp_f32_e32 v221, v221
	s_nop 0
	v_fma_f32 v201, v201, v221, -v237
	v_fma_f32 v194, v194, v221, -v238
	v_fma_f32 v207, v207, v221, -v202
	v_fma_f32 v236, v236, v221, -v224
	v_cvt_pk_bf16_f32 v86, v201, v194
	v_cvt_pk_bf16_f32 v87, v207, v236
	global_store_dwordx4 v[138:139], v[84:87], off
	v_lshlrev_b32_e32 v241, 16, v90
	v_and_b32_e32 v242, s100, v90
	v_lshlrev_b32_e32 v247, 16, v91
	v_and_b32_e32 v228, s100, v91
	v_add_f32_e32 v204, v241, v237
	v_add_f32_e32 v233, v242, v238
	v_add_f32_e32 v209, v247, v202
	v_add_f32_e32 v210, v228, v224
	v_fma_f32 v0, v134, v240, v204
	v_fma_f32 v173, v134, v225, v233
	v_fma_f32 v201, v134, v250, v209
	v_fma_f32 v194, v134, v251, v210
	v_fma_f32 v207, v135, v239, v0
	v_fma_f32 v236, v135, v177, v173
	v_fma_f32 v221, v135, v181, v201
	v_fma_f32 v193, v135, v182, v194
	v_fma_f32 v246, v136, v222, v207
	v_fma_f32 v198, v136, v223, v236
	v_fma_f32 v211, v136, v253, v221
	v_fma_f32 v240, v136, v179, v193
	s_add_i32 s101, s99, 6
	v_min_u32_e32 v225, s101, v137
	v_cvt_f32_u32_e32 v225, v225
	v_rcp_f32_e32 v225, v225
	s_nop 0
	v_fma_f32 v246, v246, v225, -v241
	v_fma_f32 v198, v198, v225, -v242
	v_fma_f32 v211, v211, v225, -v247
	v_fma_f32 v240, v240, v225, -v228
	v_cvt_pk_bf16_f32 v90, v246, v198
	v_cvt_pk_bf16_f32 v91, v211, v240
	global_store_dwordx4 v[138:139], v[88:91], off offset:2048
	v_lshl_add_u64 v[138:139], v[138:139], 0, s[26:27]
	v_lshlrev_b32_e32 v250, 16, v94
	v_and_b32_e32 v251, s100, v94
	v_lshlrev_b32_e32 v239, 16, v95
	v_and_b32_e32 v177, s100, v95
	v_add_f32_e32 v181, v250, v241
	v_add_f32_e32 v182, v251, v242
	v_add_f32_e32 v222, v239, v247
	v_add_f32_e32 v223, v177, v228
	v_fma_f32 v253, v134, v249, v181
	v_fma_f32 v179, v134, v229, v182
	v_fma_f32 v246, v134, v205, v222
	v_fma_f32 v198, v134, v206, v223
	v_fma_f32 v211, v135, v243, v253
	v_fma_f32 v240, v135, v172, v179
	v_fma_f32 v225, v135, v185, v246
	v_fma_f32 v237, v135, v186, v198
	v_fma_f32 v238, v136, v226, v211
	v_fma_f32 v202, v136, v227, v240
	v_fma_f32 v224, v136, v176, v225
	v_fma_f32 v249, v136, v183, v237
	s_add_i32 s101, s99, 7
	v_min_u32_e32 v229, s101, v137
	v_cvt_f32_u32_e32 v229, v229
	v_rcp_f32_e32 v229, v229
	s_nop 0
	v_fma_f32 v238, v238, v229, -v250
	v_fma_f32 v202, v202, v229, -v251
	v_fma_f32 v224, v224, v229, -v239
	v_fma_f32 v249, v249, v229, -v177
	v_cvt_pk_bf16_f32 v94, v238, v202
	v_cvt_pk_bf16_f32 v95, v224, v249
	global_store_dwordx4 v[138:139], v[92:95], off
	v_lshlrev_b32_e32 v205, 16, v98
	v_and_b32_e32 v206, s100, v98
	v_lshlrev_b32_e32 v243, 16, v99
	v_and_b32_e32 v172, s100, v99
	v_add_f32_e32 v185, v205, v250
	v_add_f32_e32 v186, v206, v251
	v_add_f32_e32 v226, v243, v239
	v_add_f32_e32 v227, v172, v177
	v_fma_f32 v176, v134, v204, v185
	v_fma_f32 v183, v134, v233, v186
	v_fma_f32 v238, v134, v209, v226
	v_fma_f32 v202, v134, v210, v227
	v_fma_f32 v224, v135, v252, v176
	v_fma_f32 v249, v135, v255, v183
	v_fma_f32 v229, v135, v216, v238
	v_fma_f32 v241, v135, v217, v202
	v_fma_f32 v242, v136, v230, v224
	v_fma_f32 v247, v136, v231, v249
	v_fma_f32 v228, v136, v1, v229
	v_fma_f32 v204, v136, v214, v241
	s_add_i32 s101, s99, 8
	v_min_u32_e32 v233, s101, v137
	v_cvt_f32_u32_e32 v233, v233
	v_rcp_f32_e32 v233, v233
	s_nop 0
	v_fma_f32 v242, v242, v233, -v205
	v_fma_f32 v247, v247, v233, -v206
	v_fma_f32 v228, v228, v233, -v243
	v_fma_f32 v204, v204, v233, -v172
	v_cvt_pk_bf16_f32 v98, v242, v247
	v_cvt_pk_bf16_f32 v99, v228, v204
	global_store_dwordx4 v[138:139], v[96:99], off offset:2048
	v_lshl_add_u64 v[138:139], v[138:139], 0, s[26:27]
	v_lshlrev_b32_e32 v209, 16, v102
	v_and_b32_e32 v210, s100, v102
	v_lshlrev_b32_e32 v252, 16, v103
	v_and_b32_e32 v255, s100, v103
	v_add_f32_e32 v216, v209, v205
	v_add_f32_e32 v217, v210, v206
	v_add_f32_e32 v230, v252, v243
	v_add_f32_e32 v231, v255, v172
	v_fma_f32 v1, v134, v181, v216
	v_fma_f32 v214, v134, v182, v217
	v_fma_f32 v242, v134, v222, v230
	v_fma_f32 v247, v134, v223, v231
	v_fma_f32 v228, v135, v175, v1
	v_fma_f32 v204, v135, v178, v214
	v_fma_f32 v233, v135, v197, v242
	v_fma_f32 v250, v135, v190, v247
	v_fma_f32 v251, v136, v234, v228
	v_fma_f32 v239, v136, v235, v204
	v_fma_f32 v177, v136, v254, v233
	v_fma_f32 v181, v136, v180, v250
	s_add_i32 s101, s99, 9
	v_min_u32_e32 v182, s101, v137
	v_cvt_f32_u32_e32 v182, v182
	v_rcp_f32_e32 v182, v182
	s_nop 0
	v_fma_f32 v251, v251, v182, -v209
	v_fma_f32 v239, v239, v182, -v210
	v_fma_f32 v177, v177, v182, -v252
	v_fma_f32 v181, v181, v182, -v255
	v_cvt_pk_bf16_f32 v102, v251, v239
	v_cvt_pk_bf16_f32 v103, v177, v181
	global_store_dwordx4 v[138:139], v[100:103], off
	v_lshlrev_b32_e32 v222, 16, v106
	v_and_b32_e32 v223, s100, v106
	v_lshlrev_b32_e32 v175, 16, v107
	v_and_b32_e32 v178, s100, v107
	v_add_f32_e32 v197, v222, v209
	v_add_f32_e32 v190, v223, v210
	v_add_f32_e32 v234, v175, v252
	v_add_f32_e32 v235, v178, v255
	v_fma_f32 v254, v134, v185, v197
	v_fma_f32 v180, v134, v186, v190
	v_fma_f32 v251, v134, v226, v234
	v_fma_f32 v239, v134, v227, v235
	v_fma_f32 v177, v135, v0, v254
	v_fma_f32 v181, v135, v173, v180
; __device__ __forceinline__ unsigned pk2(float lo, float hi) { return pg8::cvt_pk_bf16(lo, hi); }
; __global__ void __launch_bounds__(NTHR, 2) hybrid_fwd(Args args) {
;     ...
;         for (int i = 0; i < nr; ++i) { const int t = t_b + i;
;             const int sp = t & 2047, cnt = (sp + 1) < w ? (sp + 1) : w;
;             u32x4 qv[16];
; #pragma unroll
;             for (int j = 0; j < 16; ++j) qv[j] = qn[j];
;             if (i + 1 < nr) { const int t1 = t + 1, sp1 = t1 & 2047, c1_ = (sp1 + 1) < w ? (sp1 + 1) : w;
; #pragma unroll
;                 for (int j = 0; j < 16; ++j) qn[j] = *(const u32x4*)(UB + (size_t)(j < c1_ ? t1 - j : t1) * 512 + lane * 8); }
;             float a[8];
; #pragma unroll
;             for (int e = 0; e < 8; ++e) a[e] = 0.f;
;             const u32x4 u0 = qv[0];
; #pragma unroll
;             for (int j = 0; j < 16; ++j) { const float mk = j < cnt ? 1.0f : 0.0f; const u32x4 q = qv[j];
;                 a[0] += mk * bflo(q.x); a[1] += mk * bfhi(q.x); a[2] += mk * bflo(q.y); a[3] += mk * bfhi(q.y); a[4] += mk * bflo(q.z); a[5] += mk * bfhi(q.z); a[6] += mk * bflo(q.w); a[7] += mk * bfhi(q.w); }
;             const float ic = 1.0f / (float)cnt;
;             u32x4 o; o.x = pk2(a[0] * ic - bflo(u0.x), a[1] * ic - bfhi(u0.x)); o.y = pk2(a[2] * ic - bflo(u0.y), a[3] * ic - bfhi(u0.y));
;             o.z = pk2(a[4] * ic - bflo(u0.z), a[5] * ic - bfhi(u0.z)); o.w = pk2(a[6] * ic - bflo(u0.w), a[7] * ic - bfhi(u0.w));
;             *(u32x4*)(AD + (size_t)t * 1024 + lane * 8) = o; }
	v_fma_f32 v182, v135, v201, v251
	v_fma_f32 v205, v135, v194, v239
	v_fma_f32 v206, v136, v187, v177
	v_fma_f32 v243, v136, v199, v181
	v_fma_f32 v172, v136, v192, v182
	v_fma_f32 v185, v136, v184, v205
	s_add_i32 s101, s99, 10
	v_min_u32_e32 v186, s101, v137
	v_cvt_f32_u32_e32 v186, v186
	v_rcp_f32_e32 v186, v186
	s_nop 0
	v_fma_f32 v206, v206, v186, -v222
	v_fma_f32 v243, v243, v186, -v223
	v_fma_f32 v172, v172, v186, -v175
	v_fma_f32 v185, v185, v186, -v178
	v_cvt_pk_bf16_f32 v106, v206, v243
	v_cvt_pk_bf16_f32 v107, v172, v185
	global_store_dwordx4 v[138:139], v[104:107], off offset:2048
	v_lshl_add_u64 v[138:139], v[138:139], 0, s[26:27]
	v_lshlrev_b32_e32 v226, 16, v110
	v_and_b32_e32 v227, s100, v110
	v_lshlrev_b32_e32 v0, 16, v111
	v_and_b32_e32 v173, s100, v111
	v_add_f32_e32 v201, v226, v222
	v_add_f32_e32 v194, v227, v223
	v_add_f32_e32 v187, v0, v175
	v_add_f32_e32 v199, v173, v178
	v_fma_f32 v192, v134, v216, v201
	v_fma_f32 v184, v134, v217, v194
	v_fma_f32 v206, v134, v230, v187
	v_fma_f32 v243, v134, v231, v199
	v_fma_f32 v172, v135, v253, v192
	v_fma_f32 v185, v135, v179, v184
	v_fma_f32 v186, v135, v246, v206
	v_fma_f32 v209, v135, v198, v243
	v_fma_f32 v210, v136, v191, v172
	v_fma_f32 v252, v136, v244, v185
	v_fma_f32 v255, v136, v196, v186
	v_fma_f32 v216, v136, v215, v209
	s_add_i32 s101, s99, 11
	v_min_u32_e32 v217, s101, v137
	v_cvt_f32_u32_e32 v217, v217
	v_rcp_f32_e32 v217, v217
	s_nop 0
	v_fma_f32 v210, v210, v217, -v226
	v_fma_f32 v252, v252, v217, -v227
	v_fma_f32 v255, v255, v217, -v0
	v_fma_f32 v216, v216, v217, -v173
	v_cvt_pk_bf16_f32 v110, v210, v252
	v_cvt_pk_bf16_f32 v111, v255, v216
	global_store_dwordx4 v[138:139], v[108:111], off
	v_lshlrev_b32_e32 v230, 16, v114
	v_and_b32_e32 v231, s100, v114
	v_lshlrev_b32_e32 v253, 16, v115
	v_and_b32_e32 v179, s100, v115
	v_add_f32_e32 v246, v230, v226
	v_add_f32_e32 v198, v231, v227
	v_add_f32_e32 v191, v253, v0
	v_add_f32_e32 v244, v179, v173
	v_fma_f32 v196, v134, v197, v246
	v_fma_f32 v215, v134, v190, v198
	v_fma_f32 v210, v134, v234, v191
	v_fma_f32 v252, v134, v235, v244
	v_fma_f32 v255, v135, v176, v196
	v_fma_f32 v216, v135, v183, v215
	v_fma_f32 v217, v135, v238, v210
	v_fma_f32 v222, v135, v202, v252
	v_fma_f32 v223, v136, v195, v255
	v_fma_f32 v175, v136, v188, v216
	v_fma_f32 v178, v136, v200, v217
	v_fma_f32 v197, v136, v245, v222
	s_add_i32 s101, s99, 12
	v_min_u32_e32 v190, s101, v137
	v_cvt_f32_u32_e32 v190, v190
	v_rcp_f32_e32 v190, v190
	s_nop 0
	v_fma_f32 v223, v223, v190, -v230
	v_fma_f32 v175, v175, v190, -v231
	v_fma_f32 v178, v178, v190, -v253
	v_fma_f32 v197, v197, v190, -v179
	v_cvt_pk_bf16_f32 v114, v223, v175
	v_cvt_pk_bf16_f32 v115, v178, v197
	global_store_dwordx4 v[138:139], v[112:115], off offset:2048
	v_lshl_add_u64 v[138:139], v[138:139], 0, s[26:27]
	v_lshlrev_b32_e32 v234, 16, v118
	v_and_b32_e32 v235, s100, v118
	v_lshlrev_b32_e32 v176, 16, v119
	v_and_b32_e32 v183, s100, v119
	v_add_f32_e32 v238, v234, v230
	v_add_f32_e32 v202, v235, v231
	v_add_f32_e32 v195, v176, v253
	v_add_f32_e32 v188, v183, v179
	v_fma_f32 v200, v134, v201, v238
	v_fma_f32 v245, v134, v194, v202
	v_fma_f32 v223, v134, v187, v195
	v_fma_f32 v175, v134, v199, v188
	v_fma_f32 v178, v135, v1, v200
	v_fma_f32 v197, v135, v214, v245
	v_fma_f32 v190, v135, v242, v223
	v_fma_f32 v226, v135, v247, v175
	v_fma_f32 v227, v136, v203, v178
	v_fma_f32 v0, v136, v232, v197
	v_fma_f32 v173, v136, v208, v190
	v_fma_f32 v201, v136, v189, v226
	s_add_i32 s101, s99, 13
	v_min_u32_e32 v194, s101, v137
	v_cvt_f32_u32_e32 v194, v194
	v_rcp_f32_e32 v194, v194
; __device__ __forceinline__ unsigned pk2(float lo, float hi) { return pg8::cvt_pk_bf16(lo, hi); }
; __global__ void __launch_bounds__(NTHR, 2) hybrid_fwd(Args args) {
;     ...
;         for (int i = 0; i < nr; ++i) { const int t = t_b + i;
;             const int sp = t & 2047, cnt = (sp + 1) < w ? (sp + 1) : w;
;             u32x4 qv[16];
; #pragma unroll
;             for (int j = 0; j < 16; ++j) qv[j] = qn[j];
;             if (i + 1 < nr) { const int t1 = t + 1, sp1 = t1 & 2047, c1_ = (sp1 + 1) < w ? (sp1 + 1) : w;
; #pragma unroll
;                 for (int j = 0; j < 16; ++j) qn[j] = *(const u32x4*)(UB + (size_t)(j < c1_ ? t1 - j : t1) * 512 + lane * 8); }
;             float a[8];
; #pragma unroll
;             for (int e = 0; e < 8; ++e) a[e] = 0.f;
;             const u32x4 u0 = qv[0];
; #pragma unroll
;             for (int j = 0; j < 16; ++j) { const float mk = j < cnt ? 1.0f : 0.0f; const u32x4 q = qv[j];
;                 a[0] += mk * bflo(q.x); a[1] += mk * bfhi(q.x); a[2] += mk * bflo(q.y); a[3] += mk * bfhi(q.y); a[4] += mk * bflo(q.z); a[5] += mk * bfhi(q.z); a[6] += mk * bflo(q.w); a[7] += mk * bfhi(q.w); }
;             const float ic = 1.0f / (float)cnt;
;             u32x4 o; o.x = pk2(a[0] * ic - bflo(u0.x), a[1] * ic - bfhi(u0.x)); o.y = pk2(a[2] * ic - bflo(u0.y), a[3] * ic - bfhi(u0.y));
;             o.z = pk2(a[4] * ic - bflo(u0.z), a[5] * ic - bfhi(u0.z)); o.w = pk2(a[6] * ic - bflo(u0.w), a[7] * ic - bfhi(u0.w));
;             *(u32x4*)(AD + (size_t)t * 1024 + lane * 8) = o; }
	s_nop 0
	v_fma_f32 v227, v227, v194, -v234
	v_fma_f32 v0, v0, v194, -v235
	v_fma_f32 v173, v173, v194, -v176
	v_fma_f32 v201, v201, v194, -v183
	v_cvt_pk_bf16_f32 v118, v227, v0
	v_cvt_pk_bf16_f32 v119, v173, v201
	global_store_dwordx4 v[138:139], v[116:119], off
	v_lshlrev_b32_e32 v187, 16, v122
	v_and_b32_e32 v199, s100, v122
	v_lshlrev_b32_e32 v1, 16, v123
	v_and_b32_e32 v214, s100, v123
	v_add_f32_e32 v242, v187, v234
	v_add_f32_e32 v247, v199, v235
	v_add_f32_e32 v203, v1, v176
	v_add_f32_e32 v232, v214, v183
	v_fma_f32 v208, v134, v246, v242
	v_fma_f32 v189, v134, v198, v247
	v_fma_f32 v227, v134, v191, v203
	v_fma_f32 v0, v134, v244, v232
	v_fma_f32 v173, v135, v254, v208
	v_fma_f32 v201, v135, v180, v189
	v_fma_f32 v194, v135, v251, v227
	v_fma_f32 v230, v135, v239, v0
	v_fma_f32 v231, v136, v207, v173
	v_fma_f32 v253, v136, v236, v201
	v_fma_f32 v179, v136, v221, v194
	v_fma_f32 v246, v136, v193, v230
	s_add_i32 s101, s99, 14
	v_min_u32_e32 v198, s101, v137
	v_cvt_f32_u32_e32 v198, v198
	v_rcp_f32_e32 v198, v198
	s_nop 0
	v_fma_f32 v231, v231, v198, -v187
	v_fma_f32 v253, v253, v198, -v199
	v_fma_f32 v179, v179, v198, -v1
	v_fma_f32 v246, v246, v198, -v214
	v_cvt_pk_bf16_f32 v122, v231, v253
	v_cvt_pk_bf16_f32 v123, v179, v246
	global_store_dwordx4 v[138:139], v[120:123], off offset:2048
	v_lshl_add_u64 v[138:139], v[138:139], 0, s[26:27]
	v_lshlrev_b32_e32 v191, 16, v126
	v_and_b32_e32 v244, s100, v126
	v_lshlrev_b32_e32 v254, 16, v127
	v_and_b32_e32 v180, s100, v127
	v_add_f32_e32 v251, v191, v187
	v_add_f32_e32 v239, v244, v199
	v_add_f32_e32 v207, v254, v1
	v_add_f32_e32 v236, v180, v214
	v_fma_f32 v221, v134, v238, v251
	v_fma_f32 v193, v134, v202, v239
	v_fma_f32 v231, v134, v195, v207
	v_fma_f32 v253, v134, v188, v236
	v_fma_f32 v179, v135, v192, v221
	v_fma_f32 v246, v135, v184, v193
	v_fma_f32 v198, v135, v206, v231
	v_fma_f32 v234, v135, v243, v253
	v_fma_f32 v235, v136, v211, v179
	v_fma_f32 v176, v136, v240, v246
	v_fma_f32 v183, v136, v225, v198
	v_fma_f32 v238, v136, v237, v234
	s_add_i32 s101, s99, 15
	v_min_u32_e32 v202, s101, v137
	v_cvt_f32_u32_e32 v202, v202
	v_rcp_f32_e32 v202, v202
	s_nop 0
	v_fma_f32 v235, v235, v202, -v191
	v_fma_f32 v176, v176, v202, -v244
	v_fma_f32 v183, v183, v202, -v254
	v_fma_f32 v238, v238, v202, -v180
	v_cvt_pk_bf16_f32 v126, v235, v176
	v_cvt_pk_bf16_f32 v127, v183, v238
	global_store_dwordx4 v[138:139], v[124:127], off
	v_lshlrev_b32_e32 v195, 16, v130
	v_and_b32_e32 v188, s100, v130
	v_lshlrev_b32_e32 v192, 16, v131
	v_and_b32_e32 v184, s100, v131
	v_add_f32_e32 v206, v195, v191
	v_add_f32_e32 v243, v188, v244
	v_add_f32_e32 v211, v192, v254
	v_add_f32_e32 v240, v184, v180
	v_fma_f32 v225, v134, v242, v206
	v_fma_f32 v237, v134, v247, v243
	v_fma_f32 v235, v134, v203, v211
	v_fma_f32 v176, v134, v232, v240
	v_fma_f32 v183, v135, v196, v225
	v_fma_f32 v238, v135, v215, v237
	v_fma_f32 v202, v135, v210, v235
	v_fma_f32 v187, v135, v252, v176
	v_fma_f32 v199, v136, v224, v183
	v_fma_f32 v1, v136, v249, v238
	v_fma_f32 v214, v136, v229, v202
	v_fma_f32 v242, v136, v241, v187
	s_add_i32 s101, s99, 16
	v_min_u32_e32 v247, s101, v137
	v_cvt_f32_u32_e32 v247, v247
	v_rcp_f32_e32 v247, v247
	s_nop 0
	v_fma_f32 v199, v199, v247, -v195
	v_fma_f32 v1, v1, v247, -v188
	v_fma_f32 v214, v214, v247, -v192
	v_fma_f32 v242, v242, v247, -v184
	v_cvt_pk_bf16_f32 v130, v199, v1
	v_cvt_pk_bf16_f32 v131, v214, v242
	global_store_dwordx4 v[138:139], v[128:131], off offset:2048
	v_readlane_b32 s98, v248, 41
	s_cmp_eq_u32 s98, 1
	s_cbranch_scc1 .Lpool_late_ret
	s_branch .LBB0_377

; #define XCD_BAR() do { if (use_xcd) { xbar_target += (unsigned)(G / 8); xcd_local_bar((unsigned*)opq_ptr(args.ws) + 64 * (1 + (blk & 7)), xbar_target, wave == 0 && hw_lane() == 0); } else GRID_BAR(); } while (0)
; __device__ __forceinline__ void xcd_local_bar(unsigned* ctr, unsigned target, bool leader) {
;     asm volatile("s_waitcnt vmcnt(0) lgkmcnt(0)" ::: "memory");
;     __syncthreads();
;     if (leader) {
;         __hip_atomic_fetch_add(ctr, 1u, __ATOMIC_RELAXED, __HIP_MEMORY_SCOPE_AGENT);
;         while (__hip_atomic_load(ctr, __ATOMIC_RELAXED, __HIP_MEMORY_SCOPE_AGENT) < target) __builtin_amdgcn_s_sleep(1);
; __global__ void __launch_bounds__(NTHR, 2) hybrid_fwd(Args args) {
;     ...
;         const attn_body::AttnTensors AT{(const attn_body::bf16*)QF, (const attn_body::bf16*)KF, (const attn_body::bf16*)VF, (attn_body::bf16*)(AD + 512), LS};
;         const attn_body::StaticOrder S(G, blk);
;         attn_body::attn_phase<attn_body::StaticOrder, 40>((char*)lds, AT, S, wave);
;     }
;     XCD_BAR();
.LBB0_478:
	v_readlane_b32 s98, v248, 41
	s_cmp_lg_u32 s98, 1
	s_cbranch_scc1 .Lpool_late_ret
	v_readlane_b32 s10, v248, 40
	s_mov_b64 s[8:9], s[18:19]
	s_branch .Lpool_body
.Lpool_late_ret:
	s_mov_b32 s98, 0
	v_writelane_b32 v248, s98, 41
	s_and_b64 vcc, exec, s[12:13]
	s_cbranch_vccz .LBB0_497
	v_readlane_b32 s94, v248, 2
	s_mov_b64 s[10:11], s[18:19]
	s_and_b64 vcc, exec, s[4:5]
	s_mov_b64 s[14:15], 0
	s_mov_b32 s93, s69
	v_readlane_b32 s95, v248, 3
	s_cbranch_vccnz .LBB0_481
	v_mov_b32_e32 v0, v212
	s_nop 0
	v_cmp_eq_u32_e32 vcc, 0, v0
	s_and_b64 s[14:15], vcc, exec
